# k-block-major B (weights) layout extended to w_out, w_in even/odd, ffn down GEMM sites
# speedup vs baseline: 1.0486x; 1.0247x over previous
; #define LAS __attribute__((address_space(3)))
;     ...
;   const int lane = tid & 63, wid = __builtin_amdgcn_readfirstlane(tid >> 6), wr = wid >> 1, wc = wid & 1;
;   const int m0 = mt * 128, n0 = nt * 256;
;   const int r = lane & 31, h = lane >> 5, key = (r >> 2) & 3;
;   constexpr int STG = 24576;
;   const int rowl = lane >> 2, cch = (lane & 3) ^ ((lane >> 4) & 3);
;   const unsigned voffA = (unsigned)(rowl * lda * 2 + cch * 16), voffB = (unsigned)(rowl * K * 2 + cch * 16);
;   const char* Abase = (const char*)(A + (size_t)m0 * lda) + (size_t)(wid * 2) * 32 * lda;
;   const char* Bbase = (const char*)(Bt + (size_t)n0 * K) + (size_t)(wid * 4) * 32 * K;
;   const size_t ablk = (size_t)32 * lda, bblk = (size_t)32 * K;
;   LAS char* lds = (LAS char*)smem;
;   LAS char* ldsA = lds + (wid * 2) * 1024;
;   LAS char* ldsB = lds + 8192 + (wid * 4) * 1024;
;     ...
;   const int x0 = ((0 + h) ^ key) * 16, x1 = ((2 + h) ^ key) * 16;
;   const int a_rd = (wr * 64 + r) * 64, b_rd = 8192 + (wc * 128 + r) * 64;
;   f32x16 acc[2][4];
; #pragma unroll
;   for (int i = 0; i < 2; ++i)
; #pragma unroll
;     for (int j = 0; j < 4; ++j)
; #pragma unroll
;       for (int e = 0; e < 16; ++e) acc[i][j][e] = 0.f;
;   const int nk = K >> 5;
;   DMA_STEP_(0, 0);
;   DMA_STEP_(1, STG);
;   asm volatile("s_waitcnt vmcnt(6)" ::: "memory");
;   __builtin_amdgcn_s_barrier();
;   asm volatile("" ::: "memory");
; __global__ void __launch_bounds__(256, 2) fwd_kernel(Params p) {
;     ...
;       for (int j = slot; j < nmt * 4 / NX; j += nslot) { int mt, nt; gemm_tile_of(j, xcd, NX, 4, 4, mt, nt);
;         gemm_tile256<0>(MI, 1024, Wt, 1024, mt, nt, smem, tid, ea); }
.LBB0_20:
	s_ashr_i32 s10, s23, 31
	s_lshr_b32 s10, s10, 27
	s_add_i32 s10, s23, s10
	s_ashr_i32 s10, s10, 5
	v_readlane_b32 s11, v252, 18
	v_mov_b32_e32 v189, v188
	s_lshl_b32 s11, s10, s11
	v_readlane_b32 s12, v252, 41
	s_add_i32 s11, s11, s12
	v_readfirstlane_b32 s44, v189
	s_ashr_i32 s46, s44, 6
	s_lshl_b32 s12, s23, 7
	s_lshl_b32 s11, s11, 10
	s_and_b32 s12, s12, 0x380
	s_lshl_b32 s28, s46, 1
	s_or_b32 s12, s11, s12
	s_lshl_b32 s10, s10, 10
	s_lshl_b32 s11, s23, 5
	s_ashr_i32 s29, s28, 31
	s_sub_i32 s10, s11, s10
	s_lshl_b64 s[40:41], s[28:29], 15
	s_lshl_b32 s28, s46, 2
	s_ashr_i32 s11, s44, 1
	s_and_b32 s14, s10, 0xffffff00
	v_and_b32_e32 v0, 31, v189
	s_ashr_i32 s29, s28, 31
	s_lshl_b32 s10, s46, 12
	s_andn2_b32 s11, s11, 63
	v_lshlrev_b32_e32 v2, 4, v189
	s_ashr_i32 s13, s12, 31
	s_lshl_b64 s[42:43], s[28:29], 10
	s_add_i32 s29, s10, 16
	v_or_b32_e32 v197, s11, v0
	s_lshl_b32 s11, s46, 7
	v_bitop3_b32 v2, v2, 48, v189 bitop3:0x48
	v_lshlrev_b32_e32 v3, 9, v189
	s_ashr_i32 s15, s14, 31
	s_add_i32 s10, s29, 0x2000
	s_and_b32 s28, s11, 0x80
	s_movk_i32 s11, 0x7800
	s_lshl_b64 s[44:45], s[12:13], 11
	v_or_b32_e32 v4, s28, v0
	v_and_or_b32 v0, v3, s11, v2
	v_lshlrev_b32_e32 v10, 4, v189
	v_and_b32_e32 v10, 0x3c0, v10
	v_or_b32_e32 v10, v10, v2
	v_mov_b32_e32 v11, 0
	s_add_u32 s11, s21, s44
	s_addc_u32 s13, s22, s45
	s_add_u32 s40, s11, s40
	s_addc_u32 s41, s13, s41
	s_lshl_b64 s[44:45], s[14:15], 6
	s_add_u32 s11, s17, s44
	s_addc_u32 s13, s18, s45
	s_add_u32 s42, s11, s42
	s_addc_u32 s43, s13, s43
	s_lshl_b32 s11, s46, 11
	s_sub_i32 s13, s29, s11
	v_lshl_add_u64 v[192:193], s[40:41], 0, v[0:1]
	s_mov_b32 m0, s13
	v_lshl_add_u64 v[2:3], v[192:193], 0, s[72:73]
	global_load_lds_dwordx4 v0, s[40:41]
	s_add_i32 m0, s13, 0x400
	v_lshl_add_u64 v[194:195], s[42:43], 0, v[10:11]
	global_load_lds_dwordx4 v[2:3], off
	s_mov_b32 m0, s10
	s_nop 0
	global_load_lds_dwordx4 v[194:195], off
	global_load_lds_dwordx4 v[194:195], off offset:1024
	global_load_lds_dwordx4 v[194:195], off offset:2048
	global_load_lds_dwordx4 v[194:195], off offset:3072
	s_mov_b64 s[10:11], 0x10000
	s_mov_b64 s[10:11], 0x18000
	s_mov_b64 s[10:11], 0x8040
	s_add_i32 m0, s13, 0x6000
	v_lshl_add_u64 v[2:3], v[192:193], 0, 64
	global_load_lds_dwordx4 v[2:3], off
	v_lshl_add_u64 v[2:3], v[192:193], 0, s[10:11]
	s_add_i32 m0, s13, 0x6400
	v_bfe_u32 v196, v189, 5, 1
	global_load_lds_dwordx4 v[2:3], off
	s_add_i32 m0, s29, 0x8000
	s_mov_b32 s100, 0x10000
	v_lshl_add_u64 v[2:3], v[194:195], 0, s[100:101]
	global_load_lds_dwordx4 v[2:3], off
	global_load_lds_dwordx4 v[2:3], off offset:1024
	global_load_lds_dwordx4 v[2:3], off offset:2048
	global_load_lds_dwordx4 v[2:3], off offset:3072
	s_mov_b64 s[10:11], 0x10040
	s_mov_b64 s[10:11], 0x18040
	v_lshlrev_b32_e32 v218, 6, v4
	v_bfe_u32 v4, v189, 2, 2
	v_lshrrev_b32_e32 v5, 5, v189
	s_lshl_b32 s100, s100, 1
	v_lshl_add_u64 v[194:195], v[194:195], 0, s[100:101]
	s_waitcnt vmcnt(6)
	s_barrier
	v_bitop3_b32 v2, v196, v4, 2 bitop3:0x36
	v_bitop3_b32 v0, v5, v4, 1 bitop3:0x6c
	v_lshlrev_b32_e32 v220, 4, v2
	v_mov_b32_e32 v2, 0
	v_lshlrev_b32_e32 v219, 6, v197
	v_lshlrev_b32_e32 v0, 4, v0
	s_mov_b32 s41, 0xc000
	s_mov_b32 s40, 0
	s_mov_b32 s42, 0
	v_mov_b32_e32 v3, v2
	v_mov_b32_e32 v4, v2
	v_mov_b32_e32 v5, v2
	v_mov_b32_e32 v6, v2
	v_mov_b32_e32 v7, v2
	v_mov_b32_e32 v8, v2
	v_mov_b32_e32 v9, v2
	v_mov_b32_e32 v10, v2
	v_mov_b32_e32 v11, v2
	v_mov_b32_e32 v12, v2
	v_mov_b32_e32 v13, v2
	v_mov_b32_e32 v14, v2
	v_mov_b32_e32 v15, v2
	v_mov_b32_e32 v16, v2
	v_mov_b32_e32 v17, v2
	v_mov_b32_e32 v18, v2
	v_mov_b32_e32 v19, v2
	v_mov_b32_e32 v20, v2
	v_mov_b32_e32 v21, v2
	v_mov_b32_e32 v22, v2
	v_mov_b32_e32 v23, v2
	v_mov_b32_e32 v24, v2
	v_mov_b32_e32 v25, v2
	v_mov_b32_e32 v26, v2
	v_mov_b32_e32 v27, v2
	v_mov_b32_e32 v28, v2
	v_mov_b32_e32 v29, v2
	v_mov_b32_e32 v30, v2
	v_mov_b32_e32 v31, v2
	v_mov_b32_e32 v32, v2
	v_mov_b32_e32 v33, v2
	v_mov_b32_e32 v50, v2
	v_mov_b32_e32 v51, v2
	v_mov_b32_e32 v52, v2
	v_mov_b32_e32 v53, v2
	v_mov_b32_e32 v54, v2
	v_mov_b32_e32 v55, v2
	v_mov_b32_e32 v56, v2
	v_mov_b32_e32 v57, v2
	v_mov_b32_e32 v58, v2
	v_mov_b32_e32 v59, v2
	v_mov_b32_e32 v60, v2
	v_mov_b32_e32 v61, v2
	v_mov_b32_e32 v62, v2
	v_mov_b32_e32 v63, v2
	v_mov_b32_e32 v64, v2
	v_mov_b32_e32 v65, v2
	v_mov_b32_e32 v82, v2
	v_mov_b32_e32 v83, v2
	v_mov_b32_e32 v84, v2
	v_mov_b32_e32 v85, v2
	v_mov_b32_e32 v86, v2
	v_mov_b32_e32 v87, v2
	v_mov_b32_e32 v88, v2
	v_mov_b32_e32 v89, v2
	s_waitcnt vmcnt(0)
	v_mov_b32_e32 v90, v2
	v_mov_b32_e32 v91, v2
	v_mov_b32_e32 v92, v2
	v_mov_b32_e32 v93, v2
	v_mov_b32_e32 v94, v2
	v_mov_b32_e32 v95, v2
	v_mov_b32_e32 v96, v2
	v_mov_b32_e32 v97, v2
	v_mov_b32_e32 v34, v2
	v_mov_b32_e32 v35, v2
	v_mov_b32_e32 v36, v2
	v_mov_b32_e32 v37, v2
	v_mov_b32_e32 v38, v2
	v_mov_b32_e32 v39, v2
	v_mov_b32_e32 v40, v2
	v_mov_b32_e32 v41, v2
	v_mov_b32_e32 v42, v2
	v_mov_b32_e32 v43, v2
	v_mov_b32_e32 v44, v2
	v_mov_b32_e32 v45, v2
	v_mov_b32_e32 v46, v2
	v_mov_b32_e32 v47, v2
	v_mov_b32_e32 v48, v2
	v_mov_b32_e32 v49, v2
	v_mov_b32_e32 v66, v2
	v_mov_b32_e32 v67, v2
	v_mov_b32_e32 v68, v2
	v_mov_b32_e32 v69, v2
	v_mov_b32_e32 v70, v2
	v_mov_b32_e32 v71, v2
	v_mov_b32_e32 v72, v2
	v_mov_b32_e32 v73, v2
	v_mov_b32_e32 v74, v2
	v_mov_b32_e32 v75, v2
	v_mov_b32_e32 v76, v2
	v_mov_b32_e32 v77, v2
	v_mov_b32_e32 v78, v2
	v_mov_b32_e32 v79, v2
	v_mov_b32_e32 v80, v2
	v_mov_b32_e32 v81, v2
	v_mov_b32_e32 v98, v2
	v_mov_b32_e32 v99, v2
	v_mov_b32_e32 v100, v2
	v_mov_b32_e32 v101, v2
	v_mov_b32_e32 v102, v2
	v_mov_b32_e32 v103, v2
	v_mov_b32_e32 v104, v2
	v_mov_b32_e32 v105, v2
	v_mov_b32_e32 v106, v2
	v_mov_b32_e32 v107, v2
	v_mov_b32_e32 v108, v2
	v_mov_b32_e32 v109, v2
	v_mov_b32_e32 v110, v2
	v_mov_b32_e32 v111, v2
	v_mov_b32_e32 v112, v2
	v_mov_b32_e32 v113, v2
	v_mov_b32_e32 v114, v2
	v_mov_b32_e32 v115, v2
	v_mov_b32_e32 v116, v2
	v_mov_b32_e32 v117, v2
	v_mov_b32_e32 v118, v2
	v_mov_b32_e32 v119, v2
	v_mov_b32_e32 v120, v2
	v_mov_b32_e32 v121, v2
	v_mov_b32_e32 v122, v2
	v_mov_b32_e32 v123, v2
	v_mov_b32_e32 v124, v2
	v_mov_b32_e32 v125, v2
	v_mov_b32_e32 v126, v2
	v_mov_b32_e32 v127, v2
	v_mov_b32_e32 v128, v2
	v_mov_b32_e32 v129, v2
; #define LAS __attribute__((address_space(3)))
; DI f32x16 mfma32(bf16x8 a, bf16x8 b, f32x16 c) { return __builtin_amdgcn_mfma_f32_32x32x16_bf16(a, b, c, 0, 0, 0); }
;     ...
;   for (int kt = 0; kt < nk; ++kt) {
;     const int kn = (kt + 2 < nk) ? (kt + 2) : (nk - 1);
;     const LAS char* cur = lds + s0;
;     bf16x8 af[2][2], bfr[2][4];
; #pragma unroll
;     for (int kk = 0; kk < 2; ++kk) {
;       const int xo = kk ? x1 : x0;
;       af[kk][0] = *(const LAS bf16x8*)(cur + a_rd + xo);
;       bfr[kk][0] = *(const LAS bf16x8*)(cur + b_rd + xo);
;       bfr[kk][1] = *(const LAS bf16x8*)(cur + b_rd + 2048 + xo);
;       af[kk][1] = *(const LAS bf16x8*)(cur + a_rd + 2048 + xo);
;       bfr[kk][2] = *(const LAS bf16x8*)(cur + b_rd + 4096 + xo);
;       bfr[kk][3] = *(const LAS bf16x8*)(cur + b_rd + 6144 + xo);
;     }
;     DMA_STEP_(kn, s2);
; #pragma unroll
;     for (int kk = 0; kk < 2; ++kk) {
;       acc[0][0] = mfma32(bfr[kk][0], af[kk][0], acc[0][0]); acc[0][1] = mfma32(bfr[kk][1], af[kk][0], acc[0][1]);
;       acc[1][0] = mfma32(bfr[kk][0], af[kk][1], acc[1][0]); acc[1][1] = mfma32(bfr[kk][1], af[kk][1], acc[1][1]);
;       acc[0][2] = mfma32(bfr[kk][2], af[kk][0], acc[0][2]); acc[0][3] = mfma32(bfr[kk][3], af[kk][0], acc[0][3]);
;       acc[1][2] = mfma32(bfr[kk][2], af[kk][1], acc[1][2]); acc[1][3] = mfma32(bfr[kk][3], af[kk][1], acc[1][3]);
;     }
;     __builtin_amdgcn_sched_group_barrier(0x100, 12, 0);
;     __builtin_amdgcn_sched_group_barrier(0x010, 6, 0);
;     __builtin_amdgcn_sched_group_barrier(0x008, 16, 0);
;     asm volatile("s_waitcnt vmcnt(6) lgkmcnt(0)" ::: "memory");
;     __builtin_amdgcn_s_barrier();
;     asm volatile("" ::: "memory");
;     s0 = (s0 == 2 * STG) ? 0 : s0 + STG;
;     s2 = (s2 == 2 * STG) ? 0 : s2 + STG;
.LBB0_21:
	s_add_i32 s10, s42, 16
	v_add_u32_e32 v142, s10, v218
	v_add_u32_e32 v138, s10, v219
	v_add_u32_e32 v140, v142, v0
	s_min_u32 s10, s40, 29
	ds_read_b128 v[182:185], v140 offset:8192
	ds_read_b128 v[178:181], v140 offset:10240
	ds_read_b128 v[174:177], v140 offset:12288
	ds_read_b128 v[170:173], v140 offset:14336
	s_lshl_b32 s70, s10, 6
	v_lshl_add_u64 v[222:223], v[192:193], 0, s[70:71]
	s_add_i32 s10, s13, s41
	v_add_u32_e32 v139, v138, v0
	v_add_u32_e32 v143, v138, v220
	v_add_u32_e32 v150, v142, v220
	v_lshl_add_u64 v[224:225], v[222:223], 0, s[24:25]
	s_mov_b32 m0, s10
	ds_read_b128 v[154:157], v139
	ds_read_b128 v[158:161], v139 offset:2048
	ds_read_b128 v[138:141], v143
	ds_read_b128 v[162:165], v150 offset:8192
	ds_read_b128 v[166:169], v150 offset:10240
	ds_read_b128 v[142:145], v143 offset:2048
	ds_read_b128 v[146:149], v150 offset:12288
	ds_read_b128 v[150:153], v150 offset:14336
	global_load_lds_dwordx4 v[224:225], off
	v_lshl_add_u64 v[222:223], v[222:223], 0, s[38:39]
	s_add_i32 m0, s10, 0x400
	s_add_i32 s10, s29, s41
	global_load_lds_dwordx4 v[222:223], off
	s_mul_i32 s100, s70, 0x400
	v_lshl_add_u64 v[224:225], v[194:195], 0, s[100:101]
	s_add_i32 m0, s10, 0x2000
	s_nop 0
	global_load_lds_dwordx4 v[224:225], off
	global_load_lds_dwordx4 v[224:225], off offset:1024
	global_load_lds_dwordx4 v[224:225], off offset:2048
	global_load_lds_dwordx4 v[224:225], off offset:3072
	s_add_i32 s10, s42, 0x6000
	s_waitcnt lgkmcnt(0)
	v_mfma_f32_32x32x16_bf16 v[114:129], v[182:185], v[154:157], v[114:129]
	s_cmpk_lg_u32 s42, 0xc000
	s_cselect_b32 s42, s10, 0
	s_add_i32 s10, s41, 0x6000
	s_cmpk_lg_u32 s41, 0xc000
	s_cselect_b32 s41, s10, 0
	s_add_i32 s10, s40, 1
	s_min_u32 s10, s10, 29
	v_mfma_f32_32x32x16_bf16 v[98:113], v[178:181], v[154:157], v[98:113]
	s_add_i32 s11, s42, 16
	s_lshl_b32 s70, s10, 6
	v_lshl_add_u64 v[222:223], v[192:193], 0, s[70:71]
	s_add_i32 s10, s13, s41
	s_waitcnt vmcnt(6) lgkmcnt(0)
	s_barrier
	v_mfma_f32_32x32x16_bf16 v[66:81], v[182:185], v[158:161], v[66:81]
	v_lshl_add_u64 v[224:225], v[222:223], 0, s[24:25]
	s_mov_b32 m0, s10
	v_lshl_add_u64 v[222:223], v[222:223], 0, s[38:39]
	v_mfma_f32_32x32x16_bf16 v[34:49], v[178:181], v[158:161], v[34:49]
	v_mfma_f32_32x32x16_bf16 v[82:97], v[174:177], v[154:157], v[82:97]
	v_mfma_f32_32x32x16_bf16 v[50:65], v[170:173], v[154:157], v[50:65]
	v_mfma_f32_32x32x16_bf16 v[18:33], v[174:177], v[158:161], v[18:33]
	v_mfma_f32_32x32x16_bf16 v[2:17], v[170:173], v[158:161], v[2:17]
	v_mfma_f32_32x32x16_bf16 v[114:129], v[162:165], v[138:141], v[114:129]
	v_mfma_f32_32x32x16_bf16 v[98:113], v[166:169], v[138:141], v[98:113]
	v_mfma_f32_32x32x16_bf16 v[66:81], v[162:165], v[142:145], v[66:81]
	v_mfma_f32_32x32x16_bf16 v[34:49], v[166:169], v[142:145], v[34:49]
	v_mfma_f32_32x32x16_bf16 v[82:97], v[146:149], v[138:141], v[82:97]
	v_mfma_f32_32x32x16_bf16 v[50:65], v[150:153], v[138:141], v[50:65]
	v_add_u32_e32 v138, s11, v219
	v_add_u32_e32 v139, v138, v0
	v_mfma_f32_32x32x16_bf16 v[18:33], v[146:149], v[142:145], v[18:33]
	v_mfma_f32_32x32x16_bf16 v[2:17], v[150:153], v[142:145], v[2:17]
	v_add_u32_e32 v142, s11, v218
	v_add_u32_e32 v140, v142, v0
	v_add_u32_e32 v143, v138, v220
	v_add_u32_e32 v150, v142, v220
	ds_read_b128 v[158:161], v139
	ds_read_b128 v[182:185], v140 offset:8192
	ds_read_b128 v[178:181], v140 offset:10240
	ds_read_b128 v[162:165], v139 offset:2048
	ds_read_b128 v[174:177], v140 offset:12288
	ds_read_b128 v[170:173], v140 offset:14336
	ds_read_b128 v[138:141], v143
	ds_read_b128 v[166:169], v150 offset:8192
	ds_read_b128 v[154:157], v150 offset:10240
	ds_read_b128 v[142:145], v143 offset:2048
	ds_read_b128 v[146:149], v150 offset:12288
	ds_read_b128 v[150:153], v150 offset:14336
	global_load_lds_dwordx4 v[224:225], off
	s_add_i32 m0, s10, 0x400
	s_add_i32 s10, s29, s41
	global_load_lds_dwordx4 v[222:223], off
	s_mul_i32 s100, s70, 0x400
	v_lshl_add_u64 v[224:225], v[194:195], 0, s[100:101]
	s_add_i32 m0, s10, 0x2000
	s_nop 0
	global_load_lds_dwordx4 v[224:225], off
	global_load_lds_dwordx4 v[224:225], off offset:1024
	global_load_lds_dwordx4 v[224:225], off offset:2048
	global_load_lds_dwordx4 v[224:225], off offset:3072
	s_add_i32 s10, s42, 0x6000
	s_waitcnt lgkmcnt(0)
	v_mfma_f32_32x32x16_bf16 v[114:129], v[182:185], v[158:161], v[114:129]
	s_cmpk_lg_u32 s42, 0xc000
	s_cselect_b32 s42, s10, 0
	s_add_i32 s10, s41, 0x6000
	s_waitcnt vmcnt(6) lgkmcnt(0)
	s_barrier
	s_cmpk_lg_u32 s41, 0xc000
	v_mfma_f32_32x32x16_bf16 v[98:113], v[178:181], v[158:161], v[98:113]
	s_cselect_b32 s41, s10, 0
	s_add_i32 s40, s40, 2
	s_cmp_lg_u32 s40, 32
	v_mfma_f32_32x32x16_bf16 v[66:81], v[182:185], v[162:165], v[66:81]
	v_mfma_f32_32x32x16_bf16 v[34:49], v[178:181], v[162:165], v[34:49]
	v_mfma_f32_32x32x16_bf16 v[82:97], v[174:177], v[158:161], v[82:97]
	v_mfma_f32_32x32x16_bf16 v[50:65], v[170:173], v[158:161], v[50:65]
	v_mfma_f32_32x32x16_bf16 v[18:33], v[174:177], v[162:165], v[18:33]
	v_mfma_f32_32x32x16_bf16 v[2:17], v[170:173], v[162:165], v[2:17]
	v_mfma_f32_32x32x16_bf16 v[114:129], v[166:169], v[138:141], v[114:129]
	v_mfma_f32_32x32x16_bf16 v[98:113], v[154:157], v[138:141], v[98:113]
	v_mfma_f32_32x32x16_bf16 v[66:81], v[166:169], v[142:145], v[66:81]
	v_mfma_f32_32x32x16_bf16 v[34:49], v[154:157], v[142:145], v[34:49]
	v_mfma_f32_32x32x16_bf16 v[82:97], v[146:149], v[138:141], v[82:97]
	v_mfma_f32_32x32x16_bf16 v[50:65], v[150:153], v[138:141], v[50:65]
	v_mfma_f32_32x32x16_bf16 v[18:33], v[146:149], v[142:145], v[18:33]
	v_mfma_f32_32x32x16_bf16 v[2:17], v[150:153], v[142:145], v[2:17]
	s_cbranch_scc1 .LBB0_21
; DI unsigned pk2(float a, float b) { f32x2 v = {a, b}; bf2_t r = __builtin_convertvector(v, bf2_t); return __builtin_bit_cast(unsigned, r); }
;     ...
;   {
;     const int h = lane >> 5, cl = lane & 31;
; #pragma unroll
;     for (int i = 0; i < 2; ++i)
; #pragma unroll
;       for (int j = 0; j < 4; ++j)
; #pragma unroll
;         for (int g = 0; g < 4; ++g) {
;           u32x2 w; w.x = pk2(acc[i][j][4 * g], acc[i][j][4 * g + 1]); w.y = pk2(acc[i][j][4 * g + 2], acc[i][j][4 * g + 3]);
;           *(u32x2*)(smem + (wr * 64 + i * 32 + cl) * 528 + (wc * 128 + j * 32 + 8 * g + 4 * h) * 2) = w;
;         }
;   }
;   __syncthreads();
	v_mul_lo_u32 v0, v197, s55
	v_add_u32_e32 v0, 16, v0
	s_nop 1
	v_cvt_pk_bf16_f32 v114, v114, v115
	v_cvt_pk_bf16_f32 v115, v116, v117
	v_lshlrev_b32_e32 v116, 3, v196
	s_lshl_b32 s10, s28, 1
	v_add3_u32 v0, v0, v116, s10
	v_cvt_pk_bf16_f32 v116, v118, v119
	v_cvt_pk_bf16_f32 v117, v120, v121
	v_cvt_pk_bf16_f32 v98, v98, v99
	v_cvt_pk_bf16_f32 v99, v100, v101
	v_cvt_pk_bf16_f32 v100, v102, v103
	v_cvt_pk_bf16_f32 v101, v104, v105
	v_cvt_pk_bf16_f32 v82, v82, v83
	v_cvt_pk_bf16_f32 v83, v84, v85
	v_cvt_pk_bf16_f32 v84, v86, v87
	v_cvt_pk_bf16_f32 v85, v88, v89
	v_cvt_pk_bf16_f32 v50, v50, v51
	v_cvt_pk_bf16_f32 v51, v52, v53
	v_cvt_pk_bf16_f32 v52, v54, v55
	v_cvt_pk_bf16_f32 v53, v56, v57
	s_waitcnt vmcnt(0)
	s_barrier
	ds_write2_b64 v0, v[114:115], v[116:117] offset1:2
	v_cvt_pk_bf16_f32 v114, v122, v123
	v_cvt_pk_bf16_f32 v115, v124, v125
	v_cvt_pk_bf16_f32 v116, v126, v127
	v_cvt_pk_bf16_f32 v117, v128, v129
	ds_write2_b64 v0, v[98:99], v[100:101] offset0:8 offset1:10
	v_cvt_pk_bf16_f32 v98, v106, v107
	v_cvt_pk_bf16_f32 v99, v108, v109
	v_cvt_pk_bf16_f32 v100, v110, v111
	v_cvt_pk_bf16_f32 v101, v112, v113
	ds_write2_b64 v0, v[82:83], v[84:85] offset0:16 offset1:18
	v_cvt_pk_bf16_f32 v82, v90, v91
	v_cvt_pk_bf16_f32 v83, v92, v93
	v_cvt_pk_bf16_f32 v84, v94, v95
	v_cvt_pk_bf16_f32 v85, v96, v97
	ds_write2_b64 v0, v[50:51], v[52:53] offset0:24 offset1:26
	v_cvt_pk_bf16_f32 v50, v58, v59
	v_cvt_pk_bf16_f32 v51, v60, v61
	v_cvt_pk_bf16_f32 v52, v62, v63
	v_cvt_pk_bf16_f32 v53, v64, v65
	ds_write2_b64 v0, v[114:115], v[116:117] offset0:4 offset1:6
	ds_write2_b64 v0, v[98:99], v[100:101] offset0:12 offset1:14
	ds_write2_b64 v0, v[82:83], v[84:85] offset0:20 offset1:22
	ds_write2_b64 v0, v[50:51], v[52:53] offset0:28 offset1:30
	v_cvt_pk_bf16_f32 v50, v66, v67
	v_cvt_pk_bf16_f32 v51, v68, v69
	v_cvt_pk_bf16_f32 v52, v70, v71
	v_cvt_pk_bf16_f32 v53, v72, v73
	v_add_u32_e32 v0, 0x4000, v0
	v_cvt_pk_bf16_f32 v34, v34, v35
	v_cvt_pk_bf16_f32 v35, v36, v37
	v_cvt_pk_bf16_f32 v36, v38, v39
	v_cvt_pk_bf16_f32 v37, v40, v41
	v_cvt_pk_bf16_f32 v18, v18, v19
	v_cvt_pk_bf16_f32 v19, v20, v21
	v_cvt_pk_bf16_f32 v20, v22, v23
	v_cvt_pk_bf16_f32 v21, v24, v25
	v_cvt_pk_bf16_f32 v2, v2, v3
	v_cvt_pk_bf16_f32 v3, v4, v5
	v_cvt_pk_bf16_f32 v4, v6, v7
	v_cvt_pk_bf16_f32 v5, v8, v9
	ds_write2_b64 v0, v[50:51], v[52:53] offset0:64 offset1:66
	v_cvt_pk_bf16_f32 v50, v74, v75
	v_cvt_pk_bf16_f32 v51, v76, v77
	v_cvt_pk_bf16_f32 v52, v78, v79
	v_cvt_pk_bf16_f32 v53, v80, v81
	ds_write2_b64 v0, v[34:35], v[36:37] offset0:72 offset1:74
	v_cvt_pk_bf16_f32 v34, v42, v43
	v_cvt_pk_bf16_f32 v35, v44, v45
	v_cvt_pk_bf16_f32 v36, v46, v47
	v_cvt_pk_bf16_f32 v37, v48, v49
	ds_write2_b64 v0, v[18:19], v[20:21] offset0:80 offset1:82
	v_cvt_pk_bf16_f32 v18, v26, v27
	v_cvt_pk_bf16_f32 v19, v28, v29
	v_cvt_pk_bf16_f32 v20, v30, v31
	v_cvt_pk_bf16_f32 v21, v32, v33
	ds_write2_b64 v0, v[2:3], v[4:5] offset0:88 offset1:90
	v_cvt_pk_bf16_f32 v2, v10, v11
	v_cvt_pk_bf16_f32 v3, v12, v13
	v_cvt_pk_bf16_f32 v4, v14, v15
	v_cvt_pk_bf16_f32 v5, v16, v17
	s_lshl_b64 s[14:15], s[14:15], 1
	ds_write2_b64 v0, v[50:51], v[52:53] offset0:68 offset1:70
	ds_write2_b64 v0, v[34:35], v[36:37] offset0:76 offset1:78
	ds_write2_b64 v0, v[18:19], v[20:21] offset0:84 offset1:86
	ds_write2_b64 v0, v[2:3], v[4:5] offset0:92 offset1:94
	s_waitcnt vmcnt(0) lgkmcnt(0)
	s_barrier
; #define GAS __attribute__((address_space(1)))
;     ...
;   int tid2 = tid; asm volatile("" : "+v"(tid2));
;   if (EPI == 0) {
; #pragma unroll
;     for (int i = 0; i < 16; ++i) {
;       const int id = tid2 + 256 * i, r = id >> 5, c8 = (id & 31) * 8;
;       const u32x4 v = *(const u32x4*)(smem + r * 528 + c8 * 2);
;       *(GAS u32x4*)(ea.out + (size_t)(m0 + r) * ea.ldo + n0 + c8) = v;
;     }
	s_add_u32 s14, s19, s14
	v_lshlrev_b32_e32 v0, 4, v189
	v_and_b32_e32 v0, 0x1f0, v0
	s_addc_u32 s15, s20, s15
	v_add_u32_e32 v10, 16, v0
	v_lshl_add_u64 v[12:13], s[14:15], 0, v[0:1]
	v_ashrrev_i32_e32 v0, 5, v189
	v_mad_u64_u32 v[2:3], s[14:15], v0, s55, v[10:11]
	ds_read_b128 v[2:5], v2
	v_add_u32_e32 v6, s12, v0
	v_ashrrev_i32_e32 v7, 31, v6
	v_add_u32_e32 v0, 0x100, v189
	v_lshlrev_b64 v[6:7], 11, v[6:7]
	v_ashrrev_i32_e32 v0, 5, v0
	v_lshl_add_u64 v[14:15], v[12:13], 0, v[6:7]
	v_mad_u64_u32 v[6:7], s[14:15], v0, s55, v[10:11]
	ds_read_b128 v[6:9], v6
	s_waitcnt lgkmcnt(1)
	global_store_dwordx4 v[14:15], v[2:5], off
	v_readlane_b32 s10, v252, 12
	s_add_i32 s23, s23, s10
	v_add_u32_e32 v2, s12, v0
	v_ashrrev_i32_e32 v3, 31, v2
	v_lshlrev_b64 v[2:3], 11, v[2:3]
	v_add_u32_e32 v0, 0x200, v189
	v_lshl_add_u64 v[2:3], v[12:13], 0, v[2:3]
	v_ashrrev_i32_e32 v0, 5, v0
	s_waitcnt lgkmcnt(0)
	global_store_dwordx4 v[2:3], v[6:9], off
	v_mad_u64_u32 v[2:3], s[14:15], v0, s55, v[10:11]
	ds_read_b128 v[2:5], v2
	v_add_u32_e32 v6, s12, v0
	v_ashrrev_i32_e32 v7, 31, v6
	v_add_u32_e32 v0, 0x300, v189
	v_lshlrev_b64 v[6:7], 11, v[6:7]
	v_ashrrev_i32_e32 v0, 5, v0
	v_lshl_add_u64 v[14:15], v[12:13], 0, v[6:7]
	v_mad_u64_u32 v[6:7], s[14:15], v0, s55, v[10:11]
	ds_read_b128 v[6:9], v6
	s_waitcnt lgkmcnt(1)
	global_store_dwordx4 v[14:15], v[2:5], off
	s_cmp_ge_i32 s23, s16
	s_nop 0
	v_add_u32_e32 v2, s12, v0
	v_ashrrev_i32_e32 v3, 31, v2
	v_lshlrev_b64 v[2:3], 11, v[2:3]
	v_add_u32_e32 v0, 0x400, v189
	v_lshl_add_u64 v[2:3], v[12:13], 0, v[2:3]
	v_ashrrev_i32_e32 v0, 5, v0
	s_waitcnt lgkmcnt(0)
	global_store_dwordx4 v[2:3], v[6:9], off
	v_mad_u64_u32 v[2:3], s[14:15], v0, s55, v[10:11]
	ds_read_b128 v[2:5], v2
	v_add_u32_e32 v6, s12, v0
	v_ashrrev_i32_e32 v7, 31, v6
	v_add_u32_e32 v0, 0x500, v189
	v_lshlrev_b64 v[6:7], 11, v[6:7]
	v_ashrrev_i32_e32 v0, 5, v0
	v_lshl_add_u64 v[14:15], v[12:13], 0, v[6:7]
	v_mad_u64_u32 v[6:7], s[14:15], v0, s55, v[10:11]
	ds_read_b128 v[6:9], v6
	s_waitcnt lgkmcnt(1)
	global_store_dwordx4 v[14:15], v[2:5], off
	s_nop 1
	v_add_u32_e32 v2, s12, v0
	v_ashrrev_i32_e32 v3, 31, v2
	v_lshlrev_b64 v[2:3], 11, v[2:3]
	v_add_u32_e32 v0, 0x600, v189
	v_lshl_add_u64 v[2:3], v[12:13], 0, v[2:3]
	v_ashrrev_i32_e32 v0, 5, v0
	s_waitcnt lgkmcnt(0)
	global_store_dwordx4 v[2:3], v[6:9], off
	v_mad_u64_u32 v[2:3], s[14:15], v0, s55, v[10:11]
	ds_read_b128 v[2:5], v2
	v_add_u32_e32 v6, s12, v0
	v_ashrrev_i32_e32 v7, 31, v6
	v_add_u32_e32 v0, 0x700, v189
	v_lshlrev_b64 v[6:7], 11, v[6:7]
	v_ashrrev_i32_e32 v0, 5, v0
	v_lshl_add_u64 v[14:15], v[12:13], 0, v[6:7]
	v_mad_u64_u32 v[6:7], s[14:15], v0, s55, v[10:11]
	ds_read_b128 v[6:9], v6
	s_waitcnt lgkmcnt(1)
	global_store_dwordx4 v[14:15], v[2:5], off
	s_nop 1
	v_add_u32_e32 v2, s12, v0
	v_ashrrev_i32_e32 v3, 31, v2
	v_lshlrev_b64 v[2:3], 11, v[2:3]
	v_add_u32_e32 v0, 0x800, v189
	v_lshl_add_u64 v[2:3], v[12:13], 0, v[2:3]
	v_ashrrev_i32_e32 v0, 5, v0
	s_waitcnt lgkmcnt(0)
	global_store_dwordx4 v[2:3], v[6:9], off
	v_mad_u64_u32 v[2:3], s[14:15], v0, s55, v[10:11]
	ds_read_b128 v[2:5], v2
	v_add_u32_e32 v6, s12, v0
	v_ashrrev_i32_e32 v7, 31, v6
	v_add_u32_e32 v0, 0x900, v189
	v_lshlrev_b64 v[6:7], 11, v[6:7]
	v_ashrrev_i32_e32 v0, 5, v0
	v_lshl_add_u64 v[14:15], v[12:13], 0, v[6:7]
	v_mad_u64_u32 v[6:7], s[14:15], v0, s55, v[10:11]
	ds_read_b128 v[6:9], v6
	s_waitcnt lgkmcnt(1)
	global_store_dwordx4 v[14:15], v[2:5], off
	s_nop 1
	v_add_u32_e32 v2, s12, v0
	v_ashrrev_i32_e32 v3, 31, v2
	v_lshlrev_b64 v[2:3], 11, v[2:3]
	v_add_u32_e32 v0, 0xa00, v189
	v_lshl_add_u64 v[2:3], v[12:13], 0, v[2:3]
	v_ashrrev_i32_e32 v0, 5, v0
	s_waitcnt lgkmcnt(0)
	global_store_dwordx4 v[2:3], v[6:9], off
	v_mad_u64_u32 v[2:3], s[14:15], v0, s55, v[10:11]
	ds_read_b128 v[2:5], v2
	v_add_u32_e32 v6, s12, v0
	v_ashrrev_i32_e32 v7, 31, v6
	v_add_u32_e32 v0, 0xb00, v189
	v_lshlrev_b64 v[6:7], 11, v[6:7]
	v_ashrrev_i32_e32 v0, 5, v0
	v_lshl_add_u64 v[14:15], v[12:13], 0, v[6:7]
	v_mad_u64_u32 v[6:7], s[14:15], v0, s55, v[10:11]
	ds_read_b128 v[6:9], v6
	s_waitcnt lgkmcnt(1)
	global_store_dwordx4 v[14:15], v[2:5], off
	s_nop 1
	v_add_u32_e32 v2, s12, v0
	v_ashrrev_i32_e32 v3, 31, v2
	v_lshlrev_b64 v[2:3], 11, v[2:3]
	v_add_u32_e32 v0, 0xc00, v189
	v_lshl_add_u64 v[2:3], v[12:13], 0, v[2:3]
	v_ashrrev_i32_e32 v0, 5, v0
	s_waitcnt lgkmcnt(0)
	global_store_dwordx4 v[2:3], v[6:9], off
	v_mad_u64_u32 v[2:3], s[14:15], v0, s55, v[10:11]
	ds_read_b128 v[2:5], v2
	v_add_u32_e32 v6, s12, v0
	v_ashrrev_i32_e32 v7, 31, v6
	v_add_u32_e32 v0, 0xd00, v189
	v_lshlrev_b64 v[6:7], 11, v[6:7]
	v_ashrrev_i32_e32 v0, 5, v0
	v_lshl_add_u64 v[14:15], v[12:13], 0, v[6:7]
	v_mad_u64_u32 v[6:7], s[14:15], v0, s55, v[10:11]
	ds_read_b128 v[6:9], v6
	s_waitcnt lgkmcnt(1)
	global_store_dwordx4 v[14:15], v[2:5], off
	s_nop 1
	v_add_u32_e32 v2, s12, v0
	v_ashrrev_i32_e32 v3, 31, v2
	v_lshlrev_b64 v[2:3], 11, v[2:3]
	v_add_u32_e32 v0, 0xe00, v189
	v_lshl_add_u64 v[2:3], v[12:13], 0, v[2:3]
	v_ashrrev_i32_e32 v0, 5, v0
	s_waitcnt lgkmcnt(0)
	global_store_dwordx4 v[2:3], v[6:9], off
	v_mad_u64_u32 v[2:3], s[14:15], v0, s55, v[10:11]
	ds_read_b128 v[2:5], v2
	v_add_u32_e32 v6, s12, v0
	v_ashrrev_i32_e32 v7, 31, v6
	v_add_u32_e32 v0, 0xf00, v189
	v_lshlrev_b64 v[6:7], 11, v[6:7]
	v_ashrrev_i32_e32 v0, 5, v0
	v_lshl_add_u64 v[14:15], v[12:13], 0, v[6:7]
	v_mad_u64_u32 v[6:7], s[14:15], v0, s55, v[10:11]
	ds_read_b128 v[6:9], v6
	s_waitcnt lgkmcnt(1)
	global_store_dwordx4 v[14:15], v[2:5], off
	s_nop 1
	v_add_u32_e32 v2, s12, v0
	v_ashrrev_i32_e32 v3, 31, v2
	v_lshlrev_b64 v[2:3], 11, v[2:3]
	v_lshl_add_u64 v[2:3], v[12:13], 0, v[2:3]
	s_waitcnt lgkmcnt(0)
	global_store_dwordx4 v[2:3], v[6:9], off
	s_barrier
	s_cbranch_scc0 .LBB0_20

; #define LAS __attribute__((address_space(3)))
;     ...
;   const int lane = tid & 63, wid = __builtin_amdgcn_readfirstlane(tid >> 6), wr = wid >> 1, wc = wid & 1;
;   const int m0 = mt * 128, n0 = nt * 256;
;   const int r = lane & 31, h = lane >> 5, key = (r >> 2) & 3;
;   constexpr int STG = 24576;
;   const int rowl = lane >> 2, cch = (lane & 3) ^ ((lane >> 4) & 3);
;   const unsigned voffA = (unsigned)(rowl * lda * 2 + cch * 16), voffB = (unsigned)(rowl * K * 2 + cch * 16);
;   const char* Abase = (const char*)(A + (size_t)m0 * lda) + (size_t)(wid * 2) * 32 * lda;
;   const char* Bbase = (const char*)(Bt + (size_t)n0 * K) + (size_t)(wid * 4) * 32 * K;
;   const size_t ablk = (size_t)32 * lda, bblk = (size_t)32 * K;
;   LAS char* lds = (LAS char*)smem;
;   LAS char* ldsA = lds + (wid * 2) * 1024;
;   LAS char* ldsB = lds + 8192 + (wid * 4) * 1024;
;     ...
;   const int x0 = ((0 + h) ^ key) * 16, x1 = ((2 + h) ^ key) * 16;
;   const int a_rd = (wr * 64 + r) * 64, b_rd = 8192 + (wc * 128 + r) * 64;
;   f32x16 acc[2][4];
; #pragma unroll
;   for (int i = 0; i < 2; ++i)
; #pragma unroll
;     for (int j = 0; j < 4; ++j)
; #pragma unroll
;       for (int e = 0; e < 16; ++e) acc[i][j][e] = 0.f;
;   const int nk = K >> 5;
;   DMA_STEP_(0, 0);
;   DMA_STEP_(1, STG);
;   asm volatile("s_waitcnt vmcnt(6)" ::: "memory");
;   __builtin_amdgcn_s_barrier();
;   asm volatile("" ::: "memory");
; __global__ void __launch_bounds__(256, 2) fwd_kernel(Params p) {
;     ...
;       for (int j = slot; j < 576 * 9 / NX; j += nslot) { int mt, nt; gemm_tile_of(j, xcd, NX, 9, 9, mt, nt);
;         gemm_tile256<0>(H, 1024, WT_IN0, 1024, mt, nt, smem, tid, ea); }
.LBB0_183:
	s_mul_hi_i32 s10, s20, 0x38e38e39
	s_lshr_b32 s11, s10, 31
	s_ashr_i32 s10, s10, 4
	v_mov_b32_e32 v189, v188
	s_add_i32 s10, s10, s11
	v_readlane_b32 s12, v252, 18
	s_mul_i32 s11, s10, 0xffffffb8
	v_readfirstlane_b32 s21, v189
	s_lshl_b32 s10, s10, s12
	v_readlane_b32 s12, v252, 41
	s_ashr_i32 s44, s21, 6
	s_add_i32 s10, s10, s12
	s_lshl_b32 s12, s20, 7
	s_lshl_b32 s22, s44, 1
	s_add_i32 s11, s11, s20
	s_lshl_b32 s10, s10, 10
	s_and_b32 s12, s12, 0x380
	s_ashr_i32 s23, s22, 31
	s_or_b32 s12, s10, s12
	s_lshl_b32 s10, s11, 5
	s_lshl_b64 s[28:29], s[22:23], 15
	s_lshl_b32 s22, s44, 2
	s_ashr_i32 s11, s21, 1
	s_and_b32 s14, s10, 0xffffff00
	v_and_b32_e32 v0, 31, v189
	s_ashr_i32 s23, s22, 31
	s_lshl_b32 s10, s44, 12
	s_andn2_b32 s11, s11, 63
	v_lshlrev_b32_e32 v2, 4, v189
	s_ashr_i32 s13, s12, 31
	s_lshl_b64 s[40:41], s[22:23], 10
	s_add_i32 s22, s10, 16
	v_or_b32_e32 v197, s11, v0
	s_lshl_b32 s11, s44, 7
	v_bitop3_b32 v2, v2, 48, v189 bitop3:0x48
	v_lshlrev_b32_e32 v3, 9, v189
	s_ashr_i32 s15, s14, 31
	s_add_i32 s10, s22, 0x2000
	s_and_b32 s21, s11, 0x80
	s_movk_i32 s11, 0x7800
	s_lshl_b64 s[42:43], s[12:13], 11
	v_or_b32_e32 v4, s21, v0
	v_and_or_b32 v0, v3, s11, v2
	v_lshlrev_b32_e32 v10, 4, v189
	v_and_b32_e32 v10, 0x3c0, v10
	v_or_b32_e32 v10, v10, v2
	v_mov_b32_e32 v11, 0
	s_add_u32 s11, s18, s42
	s_addc_u32 s13, s19, s43
	s_add_u32 s28, s11, s28
	s_addc_u32 s29, s13, s29
	s_lshl_b64 s[42:43], s[14:15], 6
	v_readlane_b32 s46, v250, 18
	v_readlane_b32 s47, v250, 19
	s_add_u32 s11, s46, s42
	s_addc_u32 s13, s47, s43
	s_add_u32 s40, s11, s40
	s_addc_u32 s41, s13, s41
	s_lshl_b32 s11, s44, 11
	s_sub_i32 s13, s22, s11
	v_lshl_add_u64 v[192:193], s[28:29], 0, v[0:1]
	s_mov_b32 m0, s13
	v_lshl_add_u64 v[2:3], v[192:193], 0, s[72:73]
	global_load_lds_dwordx4 v0, s[28:29]
	s_add_i32 m0, s13, 0x400
	v_lshl_add_u64 v[194:195], s[40:41], 0, v[10:11]
	global_load_lds_dwordx4 v[2:3], off
	s_mov_b32 m0, s10
	s_nop 0
	global_load_lds_dwordx4 v[194:195], off
	global_load_lds_dwordx4 v[194:195], off offset:1024
	global_load_lds_dwordx4 v[194:195], off offset:2048
	global_load_lds_dwordx4 v[194:195], off offset:3072
	s_mov_b64 s[10:11], 0x10000
	s_mov_b64 s[10:11], 0x18000
	s_mov_b64 s[10:11], 0x8040
	s_add_i32 m0, s13, 0x6000
	v_lshl_add_u64 v[2:3], v[192:193], 0, 64
	global_load_lds_dwordx4 v[2:3], off
	v_lshl_add_u64 v[2:3], v[192:193], 0, s[10:11]
	s_add_i32 m0, s13, 0x6400
	v_bfe_u32 v196, v189, 5, 1
	global_load_lds_dwordx4 v[2:3], off
	s_add_i32 m0, s22, 0x8000
	s_mov_b32 s100, 0x24000
	v_lshl_add_u64 v[2:3], v[194:195], 0, s[100:101]
	global_load_lds_dwordx4 v[2:3], off
	global_load_lds_dwordx4 v[2:3], off offset:1024
	global_load_lds_dwordx4 v[2:3], off offset:2048
	global_load_lds_dwordx4 v[2:3], off offset:3072
	s_mov_b64 s[10:11], 0x10040
	s_mov_b64 s[10:11], 0x18040
	v_lshlrev_b32_e32 v218, 6, v4
	v_bfe_u32 v4, v189, 2, 2
	v_lshrrev_b32_e32 v5, 5, v189
	s_lshl_b32 s100, s100, 1
	v_lshl_add_u64 v[194:195], v[194:195], 0, s[100:101]
	s_waitcnt vmcnt(6)
	s_barrier
	v_bitop3_b32 v2, v196, v4, 2 bitop3:0x36
	v_bitop3_b32 v0, v5, v4, 1 bitop3:0x6c
	v_lshlrev_b32_e32 v220, 4, v2
	v_mov_b32_e32 v2, 0
	v_lshlrev_b32_e32 v219, 6, v197
	v_lshlrev_b32_e32 v0, 4, v0
	s_mov_b32 s28, 0xc000
	s_mov_b32 s23, 0
	s_mov_b32 s29, 0
	v_mov_b32_e32 v3, v2
	v_mov_b32_e32 v4, v2
	v_mov_b32_e32 v5, v2
	v_mov_b32_e32 v6, v2
	v_mov_b32_e32 v7, v2
	v_mov_b32_e32 v8, v2
	v_mov_b32_e32 v9, v2
	v_mov_b32_e32 v10, v2
	v_mov_b32_e32 v11, v2
	v_mov_b32_e32 v12, v2
	v_mov_b32_e32 v13, v2
	v_mov_b32_e32 v14, v2
	v_mov_b32_e32 v15, v2
	v_mov_b32_e32 v16, v2
	v_mov_b32_e32 v17, v2
	v_mov_b32_e32 v18, v2
	v_mov_b32_e32 v19, v2
	v_mov_b32_e32 v20, v2
	v_mov_b32_e32 v21, v2
	v_mov_b32_e32 v22, v2
	v_mov_b32_e32 v23, v2
	v_mov_b32_e32 v24, v2
	v_mov_b32_e32 v25, v2
	v_mov_b32_e32 v26, v2
	v_mov_b32_e32 v27, v2
	v_mov_b32_e32 v28, v2
	v_mov_b32_e32 v29, v2
	v_mov_b32_e32 v30, v2
	v_mov_b32_e32 v31, v2
	v_mov_b32_e32 v32, v2
	v_mov_b32_e32 v33, v2
	v_mov_b32_e32 v50, v2
	v_mov_b32_e32 v51, v2
	v_mov_b32_e32 v52, v2
	v_mov_b32_e32 v53, v2
	v_mov_b32_e32 v54, v2
	v_mov_b32_e32 v55, v2
	v_mov_b32_e32 v56, v2
	v_mov_b32_e32 v57, v2
	v_mov_b32_e32 v58, v2
	v_mov_b32_e32 v59, v2
	v_mov_b32_e32 v60, v2
	v_mov_b32_e32 v61, v2
	v_mov_b32_e32 v62, v2
	v_mov_b32_e32 v63, v2
	v_mov_b32_e32 v64, v2
	v_mov_b32_e32 v65, v2
	v_mov_b32_e32 v82, v2
	v_mov_b32_e32 v83, v2
	v_mov_b32_e32 v84, v2
	v_mov_b32_e32 v85, v2
	v_mov_b32_e32 v86, v2
	v_mov_b32_e32 v87, v2
	v_mov_b32_e32 v88, v2
	v_mov_b32_e32 v89, v2
	v_mov_b32_e32 v90, v2
	v_mov_b32_e32 v91, v2
	v_mov_b32_e32 v92, v2
	v_mov_b32_e32 v93, v2
	v_mov_b32_e32 v94, v2
	v_mov_b32_e32 v95, v2
	v_mov_b32_e32 v96, v2
	v_mov_b32_e32 v97, v2
	v_mov_b32_e32 v34, v2
	v_mov_b32_e32 v35, v2
	v_mov_b32_e32 v36, v2
	v_mov_b32_e32 v37, v2
	v_mov_b32_e32 v38, v2
	v_mov_b32_e32 v39, v2
	v_mov_b32_e32 v40, v2
	v_mov_b32_e32 v41, v2
	v_mov_b32_e32 v42, v2
	v_mov_b32_e32 v43, v2
	v_mov_b32_e32 v44, v2
	v_mov_b32_e32 v45, v2
	v_mov_b32_e32 v46, v2
	v_mov_b32_e32 v47, v2
	v_mov_b32_e32 v48, v2
	v_mov_b32_e32 v49, v2
	v_mov_b32_e32 v66, v2
	v_mov_b32_e32 v67, v2
	v_mov_b32_e32 v68, v2
	v_mov_b32_e32 v69, v2
	v_mov_b32_e32 v70, v2
	v_mov_b32_e32 v71, v2
	v_mov_b32_e32 v72, v2
	v_mov_b32_e32 v73, v2
	v_mov_b32_e32 v74, v2
	v_mov_b32_e32 v75, v2
	v_mov_b32_e32 v76, v2
	v_mov_b32_e32 v77, v2
	v_mov_b32_e32 v78, v2
	v_mov_b32_e32 v79, v2
	v_mov_b32_e32 v80, v2
	v_mov_b32_e32 v81, v2
	v_mov_b32_e32 v98, v2
	v_mov_b32_e32 v99, v2
	v_mov_b32_e32 v100, v2
	v_mov_b32_e32 v101, v2
	v_mov_b32_e32 v102, v2
	v_mov_b32_e32 v103, v2
	v_mov_b32_e32 v104, v2
	v_mov_b32_e32 v105, v2
	v_mov_b32_e32 v106, v2
	v_mov_b32_e32 v107, v2
	v_mov_b32_e32 v108, v2
	v_mov_b32_e32 v109, v2
	v_mov_b32_e32 v110, v2
	v_mov_b32_e32 v111, v2
	v_mov_b32_e32 v112, v2
	v_mov_b32_e32 v113, v2
	v_mov_b32_e32 v114, v2
	v_mov_b32_e32 v115, v2
	v_mov_b32_e32 v116, v2
	v_mov_b32_e32 v117, v2
	v_mov_b32_e32 v118, v2
	v_mov_b32_e32 v119, v2
	v_mov_b32_e32 v120, v2
	v_mov_b32_e32 v121, v2
	v_mov_b32_e32 v122, v2
	v_mov_b32_e32 v123, v2
	v_mov_b32_e32 v124, v2
	v_mov_b32_e32 v125, v2
	v_mov_b32_e32 v126, v2
	v_mov_b32_e32 v127, v2
	v_mov_b32_e32 v128, v2
	v_mov_b32_e32 v129, v2
; #define LAS __attribute__((address_space(3)))
; DI f32x16 mfma32(bf16x8 a, bf16x8 b, f32x16 c) { return __builtin_amdgcn_mfma_f32_32x32x16_bf16(a, b, c, 0, 0, 0); }
;     ...
;   for (int kt = 0; kt < nk; ++kt) {
;     const int kn = (kt + 2 < nk) ? (kt + 2) : (nk - 1);
;     const LAS char* cur = lds + s0;
;     bf16x8 af[2][2], bfr[2][4];
; #pragma unroll
;     for (int kk = 0; kk < 2; ++kk) {
;       const int xo = kk ? x1 : x0;
;       af[kk][0] = *(const LAS bf16x8*)(cur + a_rd + xo);
;       bfr[kk][0] = *(const LAS bf16x8*)(cur + b_rd + xo);
;       bfr[kk][1] = *(const LAS bf16x8*)(cur + b_rd + 2048 + xo);
;       af[kk][1] = *(const LAS bf16x8*)(cur + a_rd + 2048 + xo);
;       bfr[kk][2] = *(const LAS bf16x8*)(cur + b_rd + 4096 + xo);
;       bfr[kk][3] = *(const LAS bf16x8*)(cur + b_rd + 6144 + xo);
;     }
;     DMA_STEP_(kn, s2);
; #pragma unroll
;     for (int kk = 0; kk < 2; ++kk) {
;       acc[0][0] = mfma32(bfr[kk][0], af[kk][0], acc[0][0]); acc[0][1] = mfma32(bfr[kk][1], af[kk][0], acc[0][1]);
;       acc[1][0] = mfma32(bfr[kk][0], af[kk][1], acc[1][0]); acc[1][1] = mfma32(bfr[kk][1], af[kk][1], acc[1][1]);
;       acc[0][2] = mfma32(bfr[kk][2], af[kk][0], acc[0][2]); acc[0][3] = mfma32(bfr[kk][3], af[kk][0], acc[0][3]);
;       acc[1][2] = mfma32(bfr[kk][2], af[kk][1], acc[1][2]); acc[1][3] = mfma32(bfr[kk][3], af[kk][1], acc[1][3]);
;     }
;     __builtin_amdgcn_sched_group_barrier(0x100, 12, 0);
;     __builtin_amdgcn_sched_group_barrier(0x010, 6, 0);
;     __builtin_amdgcn_sched_group_barrier(0x008, 16, 0);
;     asm volatile("s_waitcnt vmcnt(6) lgkmcnt(0)" ::: "memory");
;     __builtin_amdgcn_s_barrier();
;     asm volatile("" ::: "memory");
;     s0 = (s0 == 2 * STG) ? 0 : s0 + STG;
;     s2 = (s2 == 2 * STG) ? 0 : s2 + STG;
.LBB0_184:
	s_add_i32 s10, s29, 16
	v_add_u32_e32 v142, s10, v218
	v_add_u32_e32 v138, s10, v219
	v_add_u32_e32 v140, v142, v0
	s_min_u32 s10, s23, 29
	ds_read_b128 v[182:185], v140 offset:8192
	ds_read_b128 v[178:181], v140 offset:10240
	ds_read_b128 v[174:177], v140 offset:12288
	ds_read_b128 v[170:173], v140 offset:14336
	s_lshl_b32 s70, s10, 6
	v_lshl_add_u64 v[222:223], v[192:193], 0, s[70:71]
	s_add_i32 s10, s13, s28
	v_add_u32_e32 v139, v138, v0
	v_add_u32_e32 v143, v138, v220
	v_add_u32_e32 v150, v142, v220
	v_lshl_add_u64 v[224:225], v[222:223], 0, s[24:25]
	s_mov_b32 m0, s10
	ds_read_b128 v[154:157], v139
	ds_read_b128 v[158:161], v139 offset:2048
	ds_read_b128 v[138:141], v143
	ds_read_b128 v[162:165], v150 offset:8192
	ds_read_b128 v[166:169], v150 offset:10240
	ds_read_b128 v[142:145], v143 offset:2048
	ds_read_b128 v[146:149], v150 offset:12288
	ds_read_b128 v[150:153], v150 offset:14336
	global_load_lds_dwordx4 v[224:225], off
	v_lshl_add_u64 v[222:223], v[222:223], 0, s[38:39]
	s_add_i32 m0, s10, 0x400
	s_add_i32 s10, s22, s28
	global_load_lds_dwordx4 v[222:223], off
	s_mul_i32 s100, s70, 0x900
	v_lshl_add_u64 v[224:225], v[194:195], 0, s[100:101]
	s_add_i32 m0, s10, 0x2000
	s_nop 0
	global_load_lds_dwordx4 v[224:225], off
	global_load_lds_dwordx4 v[224:225], off offset:1024
	global_load_lds_dwordx4 v[224:225], off offset:2048
	global_load_lds_dwordx4 v[224:225], off offset:3072
	s_add_i32 s10, s29, 0x6000
	s_waitcnt lgkmcnt(0)
	v_mfma_f32_32x32x16_bf16 v[114:129], v[182:185], v[154:157], v[114:129]
	s_cmpk_lg_u32 s29, 0xc000
	s_cselect_b32 s29, s10, 0
	s_add_i32 s10, s28, 0x6000
	s_cmpk_lg_u32 s28, 0xc000
	s_cselect_b32 s28, s10, 0
	s_add_i32 s10, s23, 1
	s_min_u32 s10, s10, 29
	v_mfma_f32_32x32x16_bf16 v[98:113], v[178:181], v[154:157], v[98:113]
	s_add_i32 s11, s29, 16
	s_lshl_b32 s70, s10, 6
	v_lshl_add_u64 v[222:223], v[192:193], 0, s[70:71]
	s_add_i32 s10, s13, s28
	s_waitcnt vmcnt(6) lgkmcnt(0)
	s_barrier
	v_mfma_f32_32x32x16_bf16 v[66:81], v[182:185], v[158:161], v[66:81]
	v_lshl_add_u64 v[224:225], v[222:223], 0, s[24:25]
	s_mov_b32 m0, s10
	v_lshl_add_u64 v[222:223], v[222:223], 0, s[38:39]
	v_mfma_f32_32x32x16_bf16 v[34:49], v[178:181], v[158:161], v[34:49]
	v_mfma_f32_32x32x16_bf16 v[82:97], v[174:177], v[154:157], v[82:97]
	v_mfma_f32_32x32x16_bf16 v[50:65], v[170:173], v[154:157], v[50:65]
	v_mfma_f32_32x32x16_bf16 v[18:33], v[174:177], v[158:161], v[18:33]
	v_mfma_f32_32x32x16_bf16 v[2:17], v[170:173], v[158:161], v[2:17]
	v_mfma_f32_32x32x16_bf16 v[114:129], v[162:165], v[138:141], v[114:129]
	v_mfma_f32_32x32x16_bf16 v[98:113], v[166:169], v[138:141], v[98:113]
	v_mfma_f32_32x32x16_bf16 v[66:81], v[162:165], v[142:145], v[66:81]
	v_mfma_f32_32x32x16_bf16 v[34:49], v[166:169], v[142:145], v[34:49]
	v_mfma_f32_32x32x16_bf16 v[82:97], v[146:149], v[138:141], v[82:97]
	v_mfma_f32_32x32x16_bf16 v[50:65], v[150:153], v[138:141], v[50:65]
	v_add_u32_e32 v138, s11, v219
	v_add_u32_e32 v139, v138, v0
	v_mfma_f32_32x32x16_bf16 v[18:33], v[146:149], v[142:145], v[18:33]
	v_mfma_f32_32x32x16_bf16 v[2:17], v[150:153], v[142:145], v[2:17]
	v_add_u32_e32 v142, s11, v218
	v_add_u32_e32 v140, v142, v0
	v_add_u32_e32 v143, v138, v220
	v_add_u32_e32 v150, v142, v220
	ds_read_b128 v[158:161], v139
	ds_read_b128 v[182:185], v140 offset:8192
	ds_read_b128 v[178:181], v140 offset:10240
	ds_read_b128 v[162:165], v139 offset:2048
	ds_read_b128 v[174:177], v140 offset:12288
	ds_read_b128 v[170:173], v140 offset:14336
	ds_read_b128 v[138:141], v143
	ds_read_b128 v[166:169], v150 offset:8192
	ds_read_b128 v[154:157], v150 offset:10240
	ds_read_b128 v[142:145], v143 offset:2048
	ds_read_b128 v[146:149], v150 offset:12288
	ds_read_b128 v[150:153], v150 offset:14336
	global_load_lds_dwordx4 v[224:225], off
	s_add_i32 m0, s10, 0x400
	s_add_i32 s10, s22, s28
	global_load_lds_dwordx4 v[222:223], off
	s_mul_i32 s100, s70, 0x900
	v_lshl_add_u64 v[224:225], v[194:195], 0, s[100:101]
	s_add_i32 m0, s10, 0x2000
	s_nop 0
	global_load_lds_dwordx4 v[224:225], off
	global_load_lds_dwordx4 v[224:225], off offset:1024
	global_load_lds_dwordx4 v[224:225], off offset:2048
	global_load_lds_dwordx4 v[224:225], off offset:3072
	s_add_i32 s10, s29, 0x6000
	s_waitcnt lgkmcnt(0)
	v_mfma_f32_32x32x16_bf16 v[114:129], v[182:185], v[158:161], v[114:129]
	s_cmpk_lg_u32 s29, 0xc000
	s_cselect_b32 s29, s10, 0
	s_add_i32 s10, s28, 0x6000
	s_waitcnt vmcnt(6) lgkmcnt(0)
	s_barrier
	s_cmpk_lg_u32 s28, 0xc000
	v_mfma_f32_32x32x16_bf16 v[98:113], v[178:181], v[158:161], v[98:113]
	s_cselect_b32 s28, s10, 0
	s_add_i32 s23, s23, 2
	s_cmp_lg_u32 s23, 32
	v_mfma_f32_32x32x16_bf16 v[66:81], v[182:185], v[162:165], v[66:81]
	v_mfma_f32_32x32x16_bf16 v[34:49], v[178:181], v[162:165], v[34:49]
	v_mfma_f32_32x32x16_bf16 v[82:97], v[174:177], v[158:161], v[82:97]
	v_mfma_f32_32x32x16_bf16 v[50:65], v[170:173], v[158:161], v[50:65]
	v_mfma_f32_32x32x16_bf16 v[18:33], v[174:177], v[162:165], v[18:33]
	v_mfma_f32_32x32x16_bf16 v[2:17], v[170:173], v[162:165], v[2:17]
	v_mfma_f32_32x32x16_bf16 v[114:129], v[166:169], v[138:141], v[114:129]
	v_mfma_f32_32x32x16_bf16 v[98:113], v[154:157], v[138:141], v[98:113]
	v_mfma_f32_32x32x16_bf16 v[66:81], v[166:169], v[142:145], v[66:81]
	v_mfma_f32_32x32x16_bf16 v[34:49], v[154:157], v[142:145], v[34:49]
	v_mfma_f32_32x32x16_bf16 v[82:97], v[146:149], v[138:141], v[82:97]
	v_mfma_f32_32x32x16_bf16 v[50:65], v[150:153], v[138:141], v[50:65]
	v_mfma_f32_32x32x16_bf16 v[18:33], v[146:149], v[142:145], v[18:33]
	v_mfma_f32_32x32x16_bf16 v[2:17], v[150:153], v[142:145], v[2:17]
	s_cbranch_scc1 .LBB0_184
; DI unsigned pk2(float a, float b) { f32x2 v = {a, b}; bf2_t r = __builtin_convertvector(v, bf2_t); return __builtin_bit_cast(unsigned, r); }
;     ...
;   {
;     const int h = lane >> 5, cl = lane & 31;
; #pragma unroll
;     for (int i = 0; i < 2; ++i)
; #pragma unroll
;       for (int j = 0; j < 4; ++j)
; #pragma unroll
;         for (int g = 0; g < 4; ++g) {
;           u32x2 w; w.x = pk2(acc[i][j][4 * g], acc[i][j][4 * g + 1]); w.y = pk2(acc[i][j][4 * g + 2], acc[i][j][4 * g + 3]);
;           *(u32x2*)(smem + (wr * 64 + i * 32 + cl) * 528 + (wc * 128 + j * 32 + 8 * g + 4 * h) * 2) = w;
;         }
;   }
;   __syncthreads();
	v_mul_lo_u32 v0, v197, s55
	v_add_u32_e32 v0, 16, v0
	s_nop 1
	v_cvt_pk_bf16_f32 v114, v114, v115
	v_cvt_pk_bf16_f32 v115, v116, v117
	v_lshlrev_b32_e32 v116, 3, v196
	s_lshl_b32 s10, s21, 1
	v_add3_u32 v0, v0, v116, s10
	v_cvt_pk_bf16_f32 v116, v118, v119
	v_cvt_pk_bf16_f32 v117, v120, v121
	v_cvt_pk_bf16_f32 v98, v98, v99
	v_cvt_pk_bf16_f32 v99, v100, v101
	v_cvt_pk_bf16_f32 v100, v102, v103
	v_cvt_pk_bf16_f32 v101, v104, v105
	v_cvt_pk_bf16_f32 v82, v82, v83
	v_cvt_pk_bf16_f32 v83, v84, v85
	v_cvt_pk_bf16_f32 v84, v86, v87
	v_cvt_pk_bf16_f32 v85, v88, v89
	v_cvt_pk_bf16_f32 v50, v50, v51
	v_cvt_pk_bf16_f32 v51, v52, v53
	v_cvt_pk_bf16_f32 v52, v54, v55
	v_cvt_pk_bf16_f32 v53, v56, v57
	s_waitcnt vmcnt(0)
	s_barrier
	ds_write2_b64 v0, v[114:115], v[116:117] offset1:2
	v_cvt_pk_bf16_f32 v114, v122, v123
	v_cvt_pk_bf16_f32 v115, v124, v125
	v_cvt_pk_bf16_f32 v116, v126, v127
	v_cvt_pk_bf16_f32 v117, v128, v129
	ds_write2_b64 v0, v[98:99], v[100:101] offset0:8 offset1:10
	v_cvt_pk_bf16_f32 v98, v106, v107
	v_cvt_pk_bf16_f32 v99, v108, v109
	v_cvt_pk_bf16_f32 v100, v110, v111
	v_cvt_pk_bf16_f32 v101, v112, v113
	ds_write2_b64 v0, v[82:83], v[84:85] offset0:16 offset1:18
	v_cvt_pk_bf16_f32 v82, v90, v91
	v_cvt_pk_bf16_f32 v83, v92, v93
	v_cvt_pk_bf16_f32 v84, v94, v95
	v_cvt_pk_bf16_f32 v85, v96, v97
	ds_write2_b64 v0, v[50:51], v[52:53] offset0:24 offset1:26
	v_cvt_pk_bf16_f32 v50, v58, v59
	v_cvt_pk_bf16_f32 v51, v60, v61
	v_cvt_pk_bf16_f32 v52, v62, v63
	v_cvt_pk_bf16_f32 v53, v64, v65
	ds_write2_b64 v0, v[114:115], v[116:117] offset0:4 offset1:6
	ds_write2_b64 v0, v[98:99], v[100:101] offset0:12 offset1:14
	ds_write2_b64 v0, v[82:83], v[84:85] offset0:20 offset1:22
	ds_write2_b64 v0, v[50:51], v[52:53] offset0:28 offset1:30
	v_cvt_pk_bf16_f32 v50, v66, v67
	v_cvt_pk_bf16_f32 v51, v68, v69
	v_cvt_pk_bf16_f32 v52, v70, v71
	v_cvt_pk_bf16_f32 v53, v72, v73
	v_add_u32_e32 v0, 0x4000, v0
	v_cvt_pk_bf16_f32 v34, v34, v35
	v_cvt_pk_bf16_f32 v35, v36, v37
	v_cvt_pk_bf16_f32 v36, v38, v39
	v_cvt_pk_bf16_f32 v37, v40, v41
	v_cvt_pk_bf16_f32 v18, v18, v19
	v_cvt_pk_bf16_f32 v19, v20, v21
	v_cvt_pk_bf16_f32 v20, v22, v23
	v_cvt_pk_bf16_f32 v21, v24, v25
	v_cvt_pk_bf16_f32 v2, v2, v3
	v_cvt_pk_bf16_f32 v3, v4, v5
	v_cvt_pk_bf16_f32 v4, v6, v7
	v_cvt_pk_bf16_f32 v5, v8, v9
	ds_write2_b64 v0, v[50:51], v[52:53] offset0:64 offset1:66
	v_cvt_pk_bf16_f32 v50, v74, v75
	v_cvt_pk_bf16_f32 v51, v76, v77
	v_cvt_pk_bf16_f32 v52, v78, v79
	v_cvt_pk_bf16_f32 v53, v80, v81
	ds_write2_b64 v0, v[34:35], v[36:37] offset0:72 offset1:74
	v_cvt_pk_bf16_f32 v34, v42, v43
	v_cvt_pk_bf16_f32 v35, v44, v45
	v_cvt_pk_bf16_f32 v36, v46, v47
	v_cvt_pk_bf16_f32 v37, v48, v49
	ds_write2_b64 v0, v[18:19], v[20:21] offset0:80 offset1:82
	v_cvt_pk_bf16_f32 v18, v26, v27
	v_cvt_pk_bf16_f32 v19, v28, v29
	v_cvt_pk_bf16_f32 v20, v30, v31
	v_cvt_pk_bf16_f32 v21, v32, v33
	ds_write2_b64 v0, v[2:3], v[4:5] offset0:88 offset1:90
	v_cvt_pk_bf16_f32 v2, v10, v11
	v_cvt_pk_bf16_f32 v3, v12, v13
	v_cvt_pk_bf16_f32 v4, v14, v15
	v_cvt_pk_bf16_f32 v5, v16, v17
	s_lshl_b64 s[14:15], s[14:15], 1
	ds_write2_b64 v0, v[50:51], v[52:53] offset0:68 offset1:70
	ds_write2_b64 v0, v[34:35], v[36:37] offset0:76 offset1:78
	ds_write2_b64 v0, v[18:19], v[20:21] offset0:84 offset1:86
	ds_write2_b64 v0, v[2:3], v[4:5] offset0:92 offset1:94
	s_waitcnt vmcnt(0) lgkmcnt(0)
	s_barrier
; #define GAS __attribute__((address_space(1)))
;     ...
;   int tid2 = tid; asm volatile("" : "+v"(tid2));
;   if (EPI == 0) {
; #pragma unroll
;     for (int i = 0; i < 16; ++i) {
;       const int id = tid2 + 256 * i, r = id >> 5, c8 = (id & 31) * 8;
;       const u32x4 v = *(const u32x4*)(smem + r * 528 + c8 * 2);
;       *(GAS u32x4*)(ea.out + (size_t)(m0 + r) * ea.ldo + n0 + c8) = v;
;     }
	s_add_u32 s14, s16, s14
	v_lshlrev_b32_e32 v0, 4, v189
	v_and_b32_e32 v0, 0x1f0, v0
	s_addc_u32 s15, s17, s15
	v_add_u32_e32 v10, 16, v0
	v_lshl_add_u64 v[12:13], s[14:15], 0, v[0:1]
	v_ashrrev_i32_e32 v0, 5, v189
	v_mad_u64_u32 v[2:3], s[14:15], v0, s55, v[10:11]
	v_add_u32_e32 v0, s12, v0
	v_mad_i64_i32 v[14:15], s[14:15], v0, s35, v[12:13]
	v_add_u32_e32 v0, 0x100, v189
	ds_read_b128 v[2:5], v2
	v_ashrrev_i32_e32 v0, 5, v0
	v_mad_u64_u32 v[6:7], s[14:15], v0, s55, v[10:11]
	ds_read_b128 v[6:9], v6
	v_add_u32_e32 v0, s12, v0
	s_waitcnt lgkmcnt(1)
	global_store_dwordx4 v[14:15], v[2:5], off
	v_readlane_b32 s10, v252, 12
	s_add_i32 s20, s20, s10
	v_mad_i64_i32 v[2:3], s[14:15], v0, s35, v[12:13]
	v_add_u32_e32 v0, 0x200, v189
	v_ashrrev_i32_e32 v0, 5, v0
	s_waitcnt lgkmcnt(0)
	global_store_dwordx4 v[2:3], v[6:9], off
	v_mad_u64_u32 v[2:3], s[14:15], v0, s55, v[10:11]
	v_add_u32_e32 v0, s12, v0
	v_mad_i64_i32 v[14:15], s[14:15], v0, s35, v[12:13]
	v_add_u32_e32 v0, 0x300, v189
	ds_read_b128 v[2:5], v2
	v_ashrrev_i32_e32 v0, 5, v0
	v_mad_u64_u32 v[6:7], s[14:15], v0, s55, v[10:11]
	ds_read_b128 v[6:9], v6
	v_add_u32_e32 v0, s12, v0
	s_waitcnt lgkmcnt(1)
	global_store_dwordx4 v[14:15], v[2:5], off
	s_cmp_ge_i32 s20, s45
	s_nop 0
	v_mad_i64_i32 v[2:3], s[14:15], v0, s35, v[12:13]
	v_add_u32_e32 v0, 0x400, v189
	v_ashrrev_i32_e32 v0, 5, v0
	s_waitcnt lgkmcnt(0)
	global_store_dwordx4 v[2:3], v[6:9], off
	v_mad_u64_u32 v[2:3], s[14:15], v0, s55, v[10:11]
	v_add_u32_e32 v0, s12, v0
	v_mad_i64_i32 v[14:15], s[14:15], v0, s35, v[12:13]
	v_add_u32_e32 v0, 0x500, v189
	ds_read_b128 v[2:5], v2
	v_ashrrev_i32_e32 v0, 5, v0
	v_mad_u64_u32 v[6:7], s[14:15], v0, s55, v[10:11]
	ds_read_b128 v[6:9], v6
	v_add_u32_e32 v0, s12, v0
	s_waitcnt lgkmcnt(1)
	global_store_dwordx4 v[14:15], v[2:5], off
	s_nop 1
	v_mad_i64_i32 v[2:3], s[14:15], v0, s35, v[12:13]
	v_add_u32_e32 v0, 0x600, v189
	v_ashrrev_i32_e32 v0, 5, v0
	s_waitcnt lgkmcnt(0)
	global_store_dwordx4 v[2:3], v[6:9], off
	v_mad_u64_u32 v[2:3], s[14:15], v0, s55, v[10:11]
	v_add_u32_e32 v0, s12, v0
	v_mad_i64_i32 v[14:15], s[14:15], v0, s35, v[12:13]
	v_add_u32_e32 v0, 0x700, v189
	ds_read_b128 v[2:5], v2
	v_ashrrev_i32_e32 v0, 5, v0
	v_mad_u64_u32 v[6:7], s[14:15], v0, s55, v[10:11]
	ds_read_b128 v[6:9], v6
	v_add_u32_e32 v0, s12, v0
	s_waitcnt lgkmcnt(1)
	global_store_dwordx4 v[14:15], v[2:5], off
	s_nop 1
	v_mad_i64_i32 v[2:3], s[14:15], v0, s35, v[12:13]
	v_add_u32_e32 v0, 0x800, v189
	v_ashrrev_i32_e32 v0, 5, v0
	s_waitcnt lgkmcnt(0)
	global_store_dwordx4 v[2:3], v[6:9], off
	v_mad_u64_u32 v[2:3], s[14:15], v0, s55, v[10:11]
	v_add_u32_e32 v0, s12, v0
	v_mad_i64_i32 v[14:15], s[14:15], v0, s35, v[12:13]
	v_add_u32_e32 v0, 0x900, v189
	ds_read_b128 v[2:5], v2
	v_ashrrev_i32_e32 v0, 5, v0
	v_mad_u64_u32 v[6:7], s[14:15], v0, s55, v[10:11]
	ds_read_b128 v[6:9], v6
	v_add_u32_e32 v0, s12, v0
	s_waitcnt lgkmcnt(1)
	global_store_dwordx4 v[14:15], v[2:5], off
	s_nop 1
	v_mad_i64_i32 v[2:3], s[14:15], v0, s35, v[12:13]
	v_add_u32_e32 v0, 0xa00, v189
	v_ashrrev_i32_e32 v0, 5, v0
	s_waitcnt lgkmcnt(0)
	global_store_dwordx4 v[2:3], v[6:9], off
	v_mad_u64_u32 v[2:3], s[14:15], v0, s55, v[10:11]
	v_add_u32_e32 v0, s12, v0
	v_mad_i64_i32 v[14:15], s[14:15], v0, s35, v[12:13]
	v_add_u32_e32 v0, 0xb00, v189
	ds_read_b128 v[2:5], v2
	v_ashrrev_i32_e32 v0, 5, v0
	v_mad_u64_u32 v[6:7], s[14:15], v0, s55, v[10:11]
	ds_read_b128 v[6:9], v6
	v_add_u32_e32 v0, s12, v0
	s_waitcnt lgkmcnt(1)
	global_store_dwordx4 v[14:15], v[2:5], off
	s_nop 1
	v_mad_i64_i32 v[2:3], s[14:15], v0, s35, v[12:13]
	v_add_u32_e32 v0, 0xc00, v189
	v_ashrrev_i32_e32 v0, 5, v0
	s_waitcnt lgkmcnt(0)
	global_store_dwordx4 v[2:3], v[6:9], off
	v_mad_u64_u32 v[2:3], s[14:15], v0, s55, v[10:11]
	v_add_u32_e32 v0, s12, v0
	v_mad_i64_i32 v[14:15], s[14:15], v0, s35, v[12:13]
	v_add_u32_e32 v0, 0xd00, v189
	ds_read_b128 v[2:5], v2
	v_ashrrev_i32_e32 v0, 5, v0
	v_mad_u64_u32 v[6:7], s[14:15], v0, s55, v[10:11]
	ds_read_b128 v[6:9], v6
	v_add_u32_e32 v0, s12, v0
	s_waitcnt lgkmcnt(1)
	global_store_dwordx4 v[14:15], v[2:5], off
	s_nop 1
	v_mad_i64_i32 v[2:3], s[14:15], v0, s35, v[12:13]
	v_add_u32_e32 v0, 0xe00, v189
	v_ashrrev_i32_e32 v0, 5, v0
	s_waitcnt lgkmcnt(0)
	global_store_dwordx4 v[2:3], v[6:9], off
	v_mad_u64_u32 v[2:3], s[14:15], v0, s55, v[10:11]
	v_add_u32_e32 v0, s12, v0
	v_mad_i64_i32 v[14:15], s[14:15], v0, s35, v[12:13]
	v_add_u32_e32 v0, 0xf00, v189
	v_ashrrev_i32_e32 v0, 5, v0
	ds_read_b128 v[2:5], v2
	v_mad_u64_u32 v[6:7], s[14:15], v0, s55, v[10:11]
	ds_read_b128 v[6:9], v6
	v_add_u32_e32 v0, s12, v0
	s_waitcnt lgkmcnt(1)
	global_store_dwordx4 v[14:15], v[2:5], off
	s_nop 1
	v_mad_i64_i32 v[2:3], s[12:13], v0, s35, v[12:13]
	s_waitcnt lgkmcnt(0)
	global_store_dwordx4 v[2:3], v[6:9], off
	s_barrier
	s_cbranch_scc0 .LBB0_183
	v_mov_b64_e32 v[6:7], v[130:131]
	v_mov_b64_e32 v[2:3], v[134:135]
	v_mov_b32_e32 v31, v214
	v_mov_b32_e32 v30, v215
	v_mov_b32_e32 v29, v216
	v_mov_b32_e32 v28, v217
	v_mov_b64_e32 v[8:9], v[132:133]
	v_mov_b64_e32 v[4:5], v[136:137]
	v_readlane_b32 s44, v250, 17

; #define LAS __attribute__((address_space(3)))
;     ...
;   const int lane = tid & 63, wid = __builtin_amdgcn_readfirstlane(tid >> 6), wr = wid >> 1, wc = wid & 1;
;   const int m0 = mt * 128, n0 = nt * 256;
;   const int r = lane & 31, h = lane >> 5, key = (r >> 2) & 3;
;   constexpr int STG = 24576;
;   const int rowl = lane >> 2, cch = (lane & 3) ^ ((lane >> 4) & 3);
;   const unsigned voffA = (unsigned)(rowl * lda * 2 + cch * 16), voffB = (unsigned)(rowl * K * 2 + cch * 16);
;   const char* Abase = (const char*)(A + (size_t)m0 * lda) + (size_t)(wid * 2) * 32 * lda;
;   const char* Bbase = (const char*)(Bt + (size_t)n0 * K) + (size_t)(wid * 4) * 32 * K;
;   const size_t ablk = (size_t)32 * lda, bblk = (size_t)32 * K;
;   LAS char* lds = (LAS char*)smem;
;   LAS char* ldsA = lds + (wid * 2) * 1024;
;   LAS char* ldsB = lds + 8192 + (wid * 4) * 1024;
;     ...
;   const int x0 = ((0 + h) ^ key) * 16, x1 = ((2 + h) ^ key) * 16;
;   const int a_rd = (wr * 64 + r) * 64, b_rd = 8192 + (wc * 128 + r) * 64;
;   f32x16 acc[2][4];
; #pragma unroll
;   for (int i = 0; i < 2; ++i)
; #pragma unroll
;     for (int j = 0; j < 4; ++j)
; #pragma unroll
;       for (int e = 0; e < 16; ++e) acc[i][j][e] = 0.f;
;   const int nk = K >> 5;
;   DMA_STEP_(0, 0);
;   DMA_STEP_(1, STG);
;   asm volatile("s_waitcnt vmcnt(6)" ::: "memory");
;   __builtin_amdgcn_s_barrier();
;   asm volatile("" ::: "memory");
; __global__ void __launch_bounds__(256, 2) fwd_kernel(Params p) {
;     ...
;         if (j < 512 * 9 / NX) gemm_tile_of(j, xcd, NX, 9, 9, mt, nt); else { mt = 512 + (j - 512 * 9 / NX) * NX + xcd; nt = 2; }
;         gemm_tile256<0>(H, 1024, WT_IN1, 1024, mt, nt, smem, tid, ea);
.LBB0_234:
	v_mov_b32_e32 v189, v188
	s_lshl_b32 s12, s23, 7
	v_readfirstlane_b32 s42, v189
	s_ashr_i32 s44, s42, 6
	s_lshl_b32 s28, s44, 2
	s_ashr_i32 s29, s28, 31
	s_lshl_b32 s23, s44, 12
	s_lshl_b64 s[40:41], s[28:29], 10
	s_add_i32 s28, s23, 16
	s_ashr_i32 s23, s42, 1
	v_and_b32_e32 v0, 31, v189
	s_andn2_b32 s23, s23, 63
	v_lshlrev_b32_e32 v2, 4, v189
	s_lshl_b32 s10, s44, 1
	v_or_b32_e32 v197, s23, v0
	s_lshl_b32 s23, s44, 7
	v_bitop3_b32 v2, v2, 48, v189 bitop3:0x48
	v_lshlrev_b32_e32 v3, 9, v189
	s_ashr_i32 s13, s12, 31
	s_ashr_i32 s11, s10, 31
	s_and_b32 s23, s23, 0x80
	s_movk_i32 s42, 0x7800
	s_lshl_b64 s[10:11], s[10:11], 15
	s_add_i32 s29, s28, 0x2000
	v_or_b32_e32 v4, s23, v0
	v_and_or_b32 v0, v3, s42, v2
	v_lshlrev_b32_e32 v10, 4, v189
	v_and_b32_e32 v10, 0x3c0, v10
	v_or_b32_e32 v10, v10, v2
	v_mov_b32_e32 v11, 0
	s_lshl_b64 s[42:43], s[12:13], 11
	s_add_u32 s13, s18, s42
	s_addc_u32 s42, s19, s43
	s_add_u32 s10, s13, s10
	s_addc_u32 s11, s42, s11
	s_lshl_b64 s[42:43], s[14:15], 6
	s_add_u32 s13, s20, s42
	s_addc_u32 s42, s21, s43
	s_add_u32 s40, s13, s40
	s_addc_u32 s41, s42, s41
	s_lshl_b32 s13, s44, 11
	s_sub_i32 s13, s28, s13
	v_lshl_add_u64 v[192:193], s[10:11], 0, v[0:1]
	s_mov_b32 m0, s13
	v_lshl_add_u64 v[2:3], v[192:193], 0, s[72:73]
	global_load_lds_dwordx4 v0, s[10:11]
	s_add_i32 m0, s13, 0x400
	v_lshl_add_u64 v[194:195], s[40:41], 0, v[10:11]
	global_load_lds_dwordx4 v[2:3], off
	s_mov_b32 m0, s29
	s_nop 0
	global_load_lds_dwordx4 v[194:195], off
	global_load_lds_dwordx4 v[194:195], off offset:1024
	global_load_lds_dwordx4 v[194:195], off offset:2048
	global_load_lds_dwordx4 v[194:195], off offset:3072
	s_mov_b64 s[10:11], 0x10000
	s_mov_b64 s[10:11], 0x18000
	s_mov_b64 s[10:11], 0x8040
	s_add_i32 m0, s13, 0x6000
	v_lshl_add_u64 v[2:3], v[192:193], 0, 64
	global_load_lds_dwordx4 v[2:3], off
	v_lshl_add_u64 v[2:3], v[192:193], 0, s[10:11]
	s_add_i32 m0, s13, 0x6400
	v_bfe_u32 v196, v189, 5, 1
	global_load_lds_dwordx4 v[2:3], off
	s_add_i32 m0, s28, 0x8000
	s_mov_b32 s100, 0x24000
	v_lshl_add_u64 v[2:3], v[194:195], 0, s[100:101]
	global_load_lds_dwordx4 v[2:3], off
	global_load_lds_dwordx4 v[2:3], off offset:1024
	global_load_lds_dwordx4 v[2:3], off offset:2048
	global_load_lds_dwordx4 v[2:3], off offset:3072
	s_mov_b64 s[10:11], 0x10040
	s_mov_b64 s[10:11], 0x18040
	v_lshlrev_b32_e32 v218, 6, v4
	v_bfe_u32 v4, v189, 2, 2
	v_lshrrev_b32_e32 v5, 5, v189
	s_lshl_b32 s100, s100, 1
	v_lshl_add_u64 v[194:195], v[194:195], 0, s[100:101]
	s_waitcnt vmcnt(6)
	s_barrier
	v_bitop3_b32 v2, v196, v4, 2 bitop3:0x36
	v_bitop3_b32 v0, v5, v4, 1 bitop3:0x6c
	v_lshlrev_b32_e32 v220, 4, v2
	v_mov_b32_e32 v2, 0
	v_lshlrev_b32_e32 v219, 6, v197
	v_lshlrev_b32_e32 v0, 4, v0
	s_mov_b32 s40, 0xc000
	s_mov_b32 s29, 0
	s_mov_b32 s41, 0
	v_mov_b32_e32 v3, v2
	v_mov_b32_e32 v4, v2
	v_mov_b32_e32 v5, v2
	v_mov_b32_e32 v6, v2
	v_mov_b32_e32 v7, v2
	v_mov_b32_e32 v8, v2
	v_mov_b32_e32 v9, v2
	v_mov_b32_e32 v10, v2
	v_mov_b32_e32 v11, v2
	v_mov_b32_e32 v12, v2
	v_mov_b32_e32 v13, v2
	v_mov_b32_e32 v14, v2
	v_mov_b32_e32 v15, v2
	v_mov_b32_e32 v16, v2
	v_mov_b32_e32 v17, v2
	v_mov_b32_e32 v18, v2
	v_mov_b32_e32 v19, v2
	v_mov_b32_e32 v20, v2
	v_mov_b32_e32 v21, v2
	v_mov_b32_e32 v22, v2
	v_mov_b32_e32 v23, v2
	v_mov_b32_e32 v24, v2
	v_mov_b32_e32 v25, v2
	v_mov_b32_e32 v26, v2
	v_mov_b32_e32 v27, v2
	v_mov_b32_e32 v28, v2
	v_mov_b32_e32 v29, v2
	v_mov_b32_e32 v30, v2
	v_mov_b32_e32 v31, v2
	v_mov_b32_e32 v32, v2
	v_mov_b32_e32 v33, v2
	v_mov_b32_e32 v50, v2
	v_mov_b32_e32 v51, v2
	v_mov_b32_e32 v52, v2
	v_mov_b32_e32 v53, v2
	v_mov_b32_e32 v54, v2
	v_mov_b32_e32 v55, v2
	v_mov_b32_e32 v56, v2
	v_mov_b32_e32 v57, v2
	v_mov_b32_e32 v58, v2
	v_mov_b32_e32 v59, v2
	v_mov_b32_e32 v60, v2
	v_mov_b32_e32 v61, v2
	v_mov_b32_e32 v62, v2
	v_mov_b32_e32 v63, v2
	v_mov_b32_e32 v64, v2
	v_mov_b32_e32 v65, v2
	v_mov_b32_e32 v82, v2
	v_mov_b32_e32 v83, v2
	v_mov_b32_e32 v84, v2
	v_mov_b32_e32 v85, v2
	v_mov_b32_e32 v86, v2
	v_mov_b32_e32 v87, v2
	v_mov_b32_e32 v88, v2
	v_mov_b32_e32 v89, v2
	v_mov_b32_e32 v90, v2
	v_mov_b32_e32 v91, v2
	v_mov_b32_e32 v92, v2
	v_mov_b32_e32 v93, v2
	v_mov_b32_e32 v94, v2
	v_mov_b32_e32 v95, v2
	v_mov_b32_e32 v96, v2
	v_mov_b32_e32 v97, v2
	v_mov_b32_e32 v34, v2
	v_mov_b32_e32 v35, v2
	v_mov_b32_e32 v36, v2
	v_mov_b32_e32 v37, v2
	v_mov_b32_e32 v38, v2
	v_mov_b32_e32 v39, v2
	v_mov_b32_e32 v40, v2
	v_mov_b32_e32 v41, v2
	v_mov_b32_e32 v42, v2
	v_mov_b32_e32 v43, v2
	v_mov_b32_e32 v44, v2
	v_mov_b32_e32 v45, v2
	v_mov_b32_e32 v46, v2
	v_mov_b32_e32 v47, v2
	v_mov_b32_e32 v48, v2
	v_mov_b32_e32 v49, v2
	v_mov_b32_e32 v66, v2
	v_mov_b32_e32 v67, v2
	v_mov_b32_e32 v68, v2
	v_mov_b32_e32 v69, v2
	v_mov_b32_e32 v70, v2
	v_mov_b32_e32 v71, v2
	v_mov_b32_e32 v72, v2
	v_mov_b32_e32 v73, v2
	v_mov_b32_e32 v74, v2
	v_mov_b32_e32 v75, v2
	v_mov_b32_e32 v76, v2
	v_mov_b32_e32 v77, v2
	v_mov_b32_e32 v78, v2
	v_mov_b32_e32 v79, v2
	v_mov_b32_e32 v80, v2
	v_mov_b32_e32 v81, v2
	v_mov_b32_e32 v98, v2
	v_mov_b32_e32 v99, v2
	v_mov_b32_e32 v100, v2
	v_mov_b32_e32 v101, v2
	v_mov_b32_e32 v102, v2
	v_mov_b32_e32 v103, v2
	v_mov_b32_e32 v104, v2
	v_mov_b32_e32 v105, v2
	v_mov_b32_e32 v106, v2
	v_mov_b32_e32 v107, v2
	v_mov_b32_e32 v108, v2
	v_mov_b32_e32 v109, v2
	v_mov_b32_e32 v110, v2
	v_mov_b32_e32 v111, v2
	v_mov_b32_e32 v112, v2
	v_mov_b32_e32 v113, v2
	v_mov_b32_e32 v114, v2
	v_mov_b32_e32 v115, v2
	v_mov_b32_e32 v116, v2
	v_mov_b32_e32 v117, v2
	v_mov_b32_e32 v118, v2
	v_mov_b32_e32 v119, v2
	v_mov_b32_e32 v120, v2
	v_mov_b32_e32 v121, v2
	v_mov_b32_e32 v122, v2
	v_mov_b32_e32 v123, v2
	v_mov_b32_e32 v124, v2
	v_mov_b32_e32 v125, v2
	v_mov_b32_e32 v126, v2
	v_mov_b32_e32 v127, v2
	v_mov_b32_e32 v128, v2
	v_mov_b32_e32 v129, v2
; #define LAS __attribute__((address_space(3)))
; DI f32x16 mfma32(bf16x8 a, bf16x8 b, f32x16 c) { return __builtin_amdgcn_mfma_f32_32x32x16_bf16(a, b, c, 0, 0, 0); }
;     ...
;   for (int kt = 0; kt < nk; ++kt) {
;     const int kn = (kt + 2 < nk) ? (kt + 2) : (nk - 1);
;     const LAS char* cur = lds + s0;
;     bf16x8 af[2][2], bfr[2][4];
; #pragma unroll
;     for (int kk = 0; kk < 2; ++kk) {
;       const int xo = kk ? x1 : x0;
;       af[kk][0] = *(const LAS bf16x8*)(cur + a_rd + xo);
;       bfr[kk][0] = *(const LAS bf16x8*)(cur + b_rd + xo);
;       bfr[kk][1] = *(const LAS bf16x8*)(cur + b_rd + 2048 + xo);
;       af[kk][1] = *(const LAS bf16x8*)(cur + a_rd + 2048 + xo);
;       bfr[kk][2] = *(const LAS bf16x8*)(cur + b_rd + 4096 + xo);
;       bfr[kk][3] = *(const LAS bf16x8*)(cur + b_rd + 6144 + xo);
;     }
;     DMA_STEP_(kn, s2);
; #pragma unroll
;     for (int kk = 0; kk < 2; ++kk) {
;       acc[0][0] = mfma32(bfr[kk][0], af[kk][0], acc[0][0]); acc[0][1] = mfma32(bfr[kk][1], af[kk][0], acc[0][1]);
;       acc[1][0] = mfma32(bfr[kk][0], af[kk][1], acc[1][0]); acc[1][1] = mfma32(bfr[kk][1], af[kk][1], acc[1][1]);
;       acc[0][2] = mfma32(bfr[kk][2], af[kk][0], acc[0][2]); acc[0][3] = mfma32(bfr[kk][3], af[kk][0], acc[0][3]);
;       acc[1][2] = mfma32(bfr[kk][2], af[kk][1], acc[1][2]); acc[1][3] = mfma32(bfr[kk][3], af[kk][1], acc[1][3]);
;     }
;     __builtin_amdgcn_sched_group_barrier(0x100, 12, 0);
;     __builtin_amdgcn_sched_group_barrier(0x010, 6, 0);
;     __builtin_amdgcn_sched_group_barrier(0x008, 16, 0);
;     asm volatile("s_waitcnt vmcnt(6) lgkmcnt(0)" ::: "memory");
;     __builtin_amdgcn_s_barrier();
;     asm volatile("" ::: "memory");
;     s0 = (s0 == 2 * STG) ? 0 : s0 + STG;
;     s2 = (s2 == 2 * STG) ? 0 : s2 + STG;
.LBB0_235:
	s_add_i32 s10, s41, 16
	v_add_u32_e32 v142, s10, v218
	v_add_u32_e32 v138, s10, v219
	v_add_u32_e32 v140, v142, v0
	s_min_u32 s10, s29, 29
	ds_read_b128 v[182:185], v140 offset:8192
	ds_read_b128 v[178:181], v140 offset:10240
	ds_read_b128 v[174:177], v140 offset:12288
	ds_read_b128 v[170:173], v140 offset:14336
	s_lshl_b32 s70, s10, 6
	v_lshl_add_u64 v[222:223], v[192:193], 0, s[70:71]
	s_add_i32 s10, s13, s40
	v_add_u32_e32 v139, v138, v0
	v_add_u32_e32 v143, v138, v220
	v_add_u32_e32 v150, v142, v220
	v_lshl_add_u64 v[224:225], v[222:223], 0, s[24:25]
	s_mov_b32 m0, s10
	ds_read_b128 v[154:157], v139
	ds_read_b128 v[158:161], v139 offset:2048
	ds_read_b128 v[138:141], v143
	ds_read_b128 v[162:165], v150 offset:8192
	ds_read_b128 v[166:169], v150 offset:10240
	ds_read_b128 v[142:145], v143 offset:2048
	ds_read_b128 v[146:149], v150 offset:12288
	ds_read_b128 v[150:153], v150 offset:14336
	global_load_lds_dwordx4 v[224:225], off
	v_lshl_add_u64 v[222:223], v[222:223], 0, s[38:39]
	s_add_i32 m0, s10, 0x400
	s_add_i32 s10, s28, s40
	global_load_lds_dwordx4 v[222:223], off
	s_mul_i32 s100, s70, 0x900
	v_lshl_add_u64 v[224:225], v[194:195], 0, s[100:101]
	s_add_i32 m0, s10, 0x2000
	s_nop 0
	global_load_lds_dwordx4 v[224:225], off
	global_load_lds_dwordx4 v[224:225], off offset:1024
	global_load_lds_dwordx4 v[224:225], off offset:2048
	global_load_lds_dwordx4 v[224:225], off offset:3072
	s_add_i32 s10, s41, 0x6000
	s_waitcnt lgkmcnt(0)
	v_mfma_f32_32x32x16_bf16 v[114:129], v[182:185], v[154:157], v[114:129]
	s_cmpk_lg_u32 s41, 0xc000
	s_cselect_b32 s41, s10, 0
	s_add_i32 s10, s40, 0x6000
	s_cmpk_lg_u32 s40, 0xc000
	s_cselect_b32 s40, s10, 0
	s_add_i32 s10, s29, 1
	s_min_u32 s10, s10, 29
	v_mfma_f32_32x32x16_bf16 v[98:113], v[178:181], v[154:157], v[98:113]
	s_add_i32 s11, s41, 16
	s_lshl_b32 s70, s10, 6
	v_lshl_add_u64 v[222:223], v[192:193], 0, s[70:71]
	s_add_i32 s10, s13, s40
	s_waitcnt vmcnt(6) lgkmcnt(0)
	s_barrier
	v_mfma_f32_32x32x16_bf16 v[66:81], v[182:185], v[158:161], v[66:81]
	v_lshl_add_u64 v[224:225], v[222:223], 0, s[24:25]
	s_mov_b32 m0, s10
	v_lshl_add_u64 v[222:223], v[222:223], 0, s[38:39]
	v_mfma_f32_32x32x16_bf16 v[34:49], v[178:181], v[158:161], v[34:49]
	v_mfma_f32_32x32x16_bf16 v[82:97], v[174:177], v[154:157], v[82:97]
	v_mfma_f32_32x32x16_bf16 v[50:65], v[170:173], v[154:157], v[50:65]
	v_mfma_f32_32x32x16_bf16 v[18:33], v[174:177], v[158:161], v[18:33]
	v_mfma_f32_32x32x16_bf16 v[2:17], v[170:173], v[158:161], v[2:17]
	v_mfma_f32_32x32x16_bf16 v[114:129], v[162:165], v[138:141], v[114:129]
	v_mfma_f32_32x32x16_bf16 v[98:113], v[166:169], v[138:141], v[98:113]
	v_mfma_f32_32x32x16_bf16 v[66:81], v[162:165], v[142:145], v[66:81]
	v_mfma_f32_32x32x16_bf16 v[34:49], v[166:169], v[142:145], v[34:49]
	v_mfma_f32_32x32x16_bf16 v[82:97], v[146:149], v[138:141], v[82:97]
	v_mfma_f32_32x32x16_bf16 v[50:65], v[150:153], v[138:141], v[50:65]
	v_add_u32_e32 v138, s11, v219
	v_add_u32_e32 v139, v138, v0
	v_mfma_f32_32x32x16_bf16 v[18:33], v[146:149], v[142:145], v[18:33]
	v_mfma_f32_32x32x16_bf16 v[2:17], v[150:153], v[142:145], v[2:17]
	v_add_u32_e32 v142, s11, v218
	v_add_u32_e32 v140, v142, v0
	v_add_u32_e32 v143, v138, v220
	v_add_u32_e32 v150, v142, v220
	ds_read_b128 v[158:161], v139
	ds_read_b128 v[182:185], v140 offset:8192
	ds_read_b128 v[178:181], v140 offset:10240
	ds_read_b128 v[162:165], v139 offset:2048
	ds_read_b128 v[174:177], v140 offset:12288
	ds_read_b128 v[170:173], v140 offset:14336
	ds_read_b128 v[138:141], v143
	ds_read_b128 v[166:169], v150 offset:8192
	ds_read_b128 v[154:157], v150 offset:10240
	ds_read_b128 v[142:145], v143 offset:2048
	ds_read_b128 v[146:149], v150 offset:12288
	ds_read_b128 v[150:153], v150 offset:14336
	global_load_lds_dwordx4 v[224:225], off
	s_add_i32 m0, s10, 0x400
	s_add_i32 s10, s28, s40
	global_load_lds_dwordx4 v[222:223], off
	s_mul_i32 s100, s70, 0x900
	v_lshl_add_u64 v[224:225], v[194:195], 0, s[100:101]
	s_add_i32 m0, s10, 0x2000
	s_nop 0
	global_load_lds_dwordx4 v[224:225], off
	global_load_lds_dwordx4 v[224:225], off offset:1024
	global_load_lds_dwordx4 v[224:225], off offset:2048
	global_load_lds_dwordx4 v[224:225], off offset:3072
	s_add_i32 s10, s41, 0x6000
	s_waitcnt lgkmcnt(0)
	v_mfma_f32_32x32x16_bf16 v[114:129], v[182:185], v[158:161], v[114:129]
	s_cmpk_lg_u32 s41, 0xc000
	s_cselect_b32 s41, s10, 0
	s_add_i32 s10, s40, 0x6000
	s_waitcnt vmcnt(6) lgkmcnt(0)
	s_barrier
	s_cmpk_lg_u32 s40, 0xc000
	v_mfma_f32_32x32x16_bf16 v[98:113], v[178:181], v[158:161], v[98:113]
	s_cselect_b32 s40, s10, 0
	s_add_i32 s29, s29, 2
	s_cmp_lg_u32 s29, 32
	v_mfma_f32_32x32x16_bf16 v[66:81], v[182:185], v[162:165], v[66:81]
	v_mfma_f32_32x32x16_bf16 v[34:49], v[178:181], v[162:165], v[34:49]
	v_mfma_f32_32x32x16_bf16 v[82:97], v[174:177], v[158:161], v[82:97]
	v_mfma_f32_32x32x16_bf16 v[50:65], v[170:173], v[158:161], v[50:65]
	v_mfma_f32_32x32x16_bf16 v[18:33], v[174:177], v[162:165], v[18:33]
	v_mfma_f32_32x32x16_bf16 v[2:17], v[170:173], v[162:165], v[2:17]
	v_mfma_f32_32x32x16_bf16 v[114:129], v[166:169], v[138:141], v[114:129]
	v_mfma_f32_32x32x16_bf16 v[98:113], v[154:157], v[138:141], v[98:113]
	v_mfma_f32_32x32x16_bf16 v[66:81], v[166:169], v[142:145], v[66:81]
	v_mfma_f32_32x32x16_bf16 v[34:49], v[154:157], v[142:145], v[34:49]
	v_mfma_f32_32x32x16_bf16 v[82:97], v[146:149], v[138:141], v[82:97]
	v_mfma_f32_32x32x16_bf16 v[50:65], v[150:153], v[138:141], v[50:65]
	v_mfma_f32_32x32x16_bf16 v[18:33], v[146:149], v[142:145], v[18:33]
	v_mfma_f32_32x32x16_bf16 v[2:17], v[150:153], v[142:145], v[2:17]
	s_cbranch_scc1 .LBB0_235
; DI unsigned pk2(float a, float b) { f32x2 v = {a, b}; bf2_t r = __builtin_convertvector(v, bf2_t); return __builtin_bit_cast(unsigned, r); }
;     ...
;   {
;     const int h = lane >> 5, cl = lane & 31;
; #pragma unroll
;     for (int i = 0; i < 2; ++i)
; #pragma unroll
;       for (int j = 0; j < 4; ++j)
; #pragma unroll
;         for (int g = 0; g < 4; ++g) {
;           u32x2 w; w.x = pk2(acc[i][j][4 * g], acc[i][j][4 * g + 1]); w.y = pk2(acc[i][j][4 * g + 2], acc[i][j][4 * g + 3]);
;           *(u32x2*)(smem + (wr * 64 + i * 32 + cl) * 528 + (wc * 128 + j * 32 + 8 * g + 4 * h) * 2) = w;
;         }
;   }
;   __syncthreads();
	v_mul_lo_u32 v0, v197, s55
	v_add_u32_e32 v0, 16, v0
	s_nop 1
	v_cvt_pk_bf16_f32 v114, v114, v115
	v_cvt_pk_bf16_f32 v115, v116, v117
	v_lshlrev_b32_e32 v116, 3, v196
	s_lshl_b32 s10, s23, 1
	v_add3_u32 v0, v0, v116, s10
	v_cvt_pk_bf16_f32 v116, v118, v119
	v_cvt_pk_bf16_f32 v117, v120, v121
	v_cvt_pk_bf16_f32 v98, v98, v99
	v_cvt_pk_bf16_f32 v99, v100, v101
	v_cvt_pk_bf16_f32 v100, v102, v103
	v_cvt_pk_bf16_f32 v101, v104, v105
	v_cvt_pk_bf16_f32 v82, v82, v83
	v_cvt_pk_bf16_f32 v83, v84, v85
	v_cvt_pk_bf16_f32 v84, v86, v87
	v_cvt_pk_bf16_f32 v85, v88, v89
	v_cvt_pk_bf16_f32 v50, v50, v51
	v_cvt_pk_bf16_f32 v51, v52, v53
	v_cvt_pk_bf16_f32 v52, v54, v55
	v_cvt_pk_bf16_f32 v53, v56, v57
	s_waitcnt vmcnt(0)
	s_barrier
	ds_write2_b64 v0, v[114:115], v[116:117] offset1:2
	v_cvt_pk_bf16_f32 v114, v122, v123
	v_cvt_pk_bf16_f32 v115, v124, v125
	v_cvt_pk_bf16_f32 v116, v126, v127
	v_cvt_pk_bf16_f32 v117, v128, v129
	ds_write2_b64 v0, v[98:99], v[100:101] offset0:8 offset1:10
	v_cvt_pk_bf16_f32 v98, v106, v107
	v_cvt_pk_bf16_f32 v99, v108, v109
	v_cvt_pk_bf16_f32 v100, v110, v111
	v_cvt_pk_bf16_f32 v101, v112, v113
	ds_write2_b64 v0, v[82:83], v[84:85] offset0:16 offset1:18
	v_cvt_pk_bf16_f32 v82, v90, v91
	v_cvt_pk_bf16_f32 v83, v92, v93
	v_cvt_pk_bf16_f32 v84, v94, v95
	v_cvt_pk_bf16_f32 v85, v96, v97
	ds_write2_b64 v0, v[50:51], v[52:53] offset0:24 offset1:26
	v_cvt_pk_bf16_f32 v50, v58, v59
	v_cvt_pk_bf16_f32 v51, v60, v61
	v_cvt_pk_bf16_f32 v52, v62, v63
	v_cvt_pk_bf16_f32 v53, v64, v65
	ds_write2_b64 v0, v[114:115], v[116:117] offset0:4 offset1:6
	ds_write2_b64 v0, v[98:99], v[100:101] offset0:12 offset1:14
	ds_write2_b64 v0, v[82:83], v[84:85] offset0:20 offset1:22
	ds_write2_b64 v0, v[50:51], v[52:53] offset0:28 offset1:30
	v_cvt_pk_bf16_f32 v50, v66, v67
	v_cvt_pk_bf16_f32 v51, v68, v69
	v_cvt_pk_bf16_f32 v52, v70, v71
	v_cvt_pk_bf16_f32 v53, v72, v73
	v_add_u32_e32 v0, 0x4000, v0
	v_cvt_pk_bf16_f32 v34, v34, v35
	v_cvt_pk_bf16_f32 v35, v36, v37
	v_cvt_pk_bf16_f32 v36, v38, v39
	v_cvt_pk_bf16_f32 v37, v40, v41
	v_cvt_pk_bf16_f32 v18, v18, v19
	v_cvt_pk_bf16_f32 v19, v20, v21
	v_cvt_pk_bf16_f32 v20, v22, v23
	v_cvt_pk_bf16_f32 v21, v24, v25
	v_cvt_pk_bf16_f32 v2, v2, v3
	v_cvt_pk_bf16_f32 v3, v4, v5
	v_cvt_pk_bf16_f32 v4, v6, v7
	v_cvt_pk_bf16_f32 v5, v8, v9
	ds_write2_b64 v0, v[50:51], v[52:53] offset0:64 offset1:66
	v_cvt_pk_bf16_f32 v50, v74, v75
	v_cvt_pk_bf16_f32 v51, v76, v77
	v_cvt_pk_bf16_f32 v52, v78, v79
	v_cvt_pk_bf16_f32 v53, v80, v81
	ds_write2_b64 v0, v[34:35], v[36:37] offset0:72 offset1:74
	v_cvt_pk_bf16_f32 v34, v42, v43
	v_cvt_pk_bf16_f32 v35, v44, v45
	v_cvt_pk_bf16_f32 v36, v46, v47
	v_cvt_pk_bf16_f32 v37, v48, v49
	ds_write2_b64 v0, v[18:19], v[20:21] offset0:80 offset1:82
	v_cvt_pk_bf16_f32 v18, v26, v27
	v_cvt_pk_bf16_f32 v19, v28, v29
	v_cvt_pk_bf16_f32 v20, v30, v31
	v_cvt_pk_bf16_f32 v21, v32, v33
	ds_write2_b64 v0, v[2:3], v[4:5] offset0:88 offset1:90
	v_cvt_pk_bf16_f32 v2, v10, v11
	v_cvt_pk_bf16_f32 v3, v12, v13
	v_cvt_pk_bf16_f32 v4, v14, v15
	v_cvt_pk_bf16_f32 v5, v16, v17
	s_lshl_b64 s[10:11], s[14:15], 1
	ds_write2_b64 v0, v[50:51], v[52:53] offset0:68 offset1:70
	ds_write2_b64 v0, v[34:35], v[36:37] offset0:76 offset1:78
	ds_write2_b64 v0, v[18:19], v[20:21] offset0:84 offset1:86
	ds_write2_b64 v0, v[2:3], v[4:5] offset0:92 offset1:94
	s_waitcnt vmcnt(0) lgkmcnt(0)
	s_barrier
; #define GAS __attribute__((address_space(1)))
;     ...
;   int tid2 = tid; asm volatile("" : "+v"(tid2));
;   if (EPI == 0) {
; #pragma unroll
;     for (int i = 0; i < 16; ++i) {
;       const int id = tid2 + 256 * i, r = id >> 5, c8 = (id & 31) * 8;
;       const u32x4 v = *(const u32x4*)(smem + r * 528 + c8 * 2);
;       *(GAS u32x4*)(ea.out + (size_t)(m0 + r) * ea.ldo + n0 + c8) = v;
;     }
	s_add_u32 s10, s16, s10
	v_lshlrev_b32_e32 v0, 4, v189
	v_and_b32_e32 v0, 0x1f0, v0
	s_addc_u32 s11, s17, s11
	v_add_u32_e32 v10, 16, v0
	v_lshl_add_u64 v[12:13], s[10:11], 0, v[0:1]
	v_ashrrev_i32_e32 v0, 5, v189
	v_mad_u64_u32 v[2:3], s[10:11], v0, s55, v[10:11]
	v_add_u32_e32 v0, s12, v0
	v_mad_i64_i32 v[14:15], s[10:11], v0, s35, v[12:13]
	v_add_u32_e32 v0, 0x100, v189
	ds_read_b128 v[2:5], v2
	v_ashrrev_i32_e32 v0, 5, v0
	v_mad_u64_u32 v[6:7], s[10:11], v0, s55, v[10:11]
	ds_read_b128 v[6:9], v6
	v_add_u32_e32 v0, s12, v0
	s_waitcnt lgkmcnt(1)
	global_store_dwordx4 v[14:15], v[2:5], off
	s_nop 1
	v_mad_i64_i32 v[2:3], s[10:11], v0, s35, v[12:13]
	v_add_u32_e32 v0, 0x200, v189
	v_ashrrev_i32_e32 v0, 5, v0
	s_waitcnt lgkmcnt(0)
	global_store_dwordx4 v[2:3], v[6:9], off
	v_mad_u64_u32 v[2:3], s[10:11], v0, s55, v[10:11]
	v_add_u32_e32 v0, s12, v0
	v_mad_i64_i32 v[14:15], s[10:11], v0, s35, v[12:13]
	v_add_u32_e32 v0, 0x300, v189
	ds_read_b128 v[2:5], v2
	v_ashrrev_i32_e32 v0, 5, v0
	v_mad_u64_u32 v[6:7], s[10:11], v0, s55, v[10:11]
	ds_read_b128 v[6:9], v6
	v_add_u32_e32 v0, s12, v0
	s_waitcnt lgkmcnt(1)
	global_store_dwordx4 v[14:15], v[2:5], off
	s_nop 1
	v_mad_i64_i32 v[2:3], s[10:11], v0, s35, v[12:13]
	v_add_u32_e32 v0, 0x400, v189
	v_ashrrev_i32_e32 v0, 5, v0
	s_waitcnt lgkmcnt(0)
	global_store_dwordx4 v[2:3], v[6:9], off
	v_mad_u64_u32 v[2:3], s[10:11], v0, s55, v[10:11]
	v_add_u32_e32 v0, s12, v0
	v_mad_i64_i32 v[14:15], s[10:11], v0, s35, v[12:13]
	v_add_u32_e32 v0, 0x500, v189
	ds_read_b128 v[2:5], v2
	v_ashrrev_i32_e32 v0, 5, v0
	v_mad_u64_u32 v[6:7], s[10:11], v0, s55, v[10:11]
	ds_read_b128 v[6:9], v6
	v_add_u32_e32 v0, s12, v0
	s_waitcnt lgkmcnt(1)
	global_store_dwordx4 v[14:15], v[2:5], off
	s_nop 1
	v_mad_i64_i32 v[2:3], s[10:11], v0, s35, v[12:13]
	v_add_u32_e32 v0, 0x600, v189
	v_ashrrev_i32_e32 v0, 5, v0
	s_waitcnt lgkmcnt(0)
	global_store_dwordx4 v[2:3], v[6:9], off
	v_mad_u64_u32 v[2:3], s[10:11], v0, s55, v[10:11]
	v_add_u32_e32 v0, s12, v0
	v_mad_i64_i32 v[14:15], s[10:11], v0, s35, v[12:13]
	v_add_u32_e32 v0, 0x700, v189
	ds_read_b128 v[2:5], v2
	v_ashrrev_i32_e32 v0, 5, v0
	v_mad_u64_u32 v[6:7], s[10:11], v0, s55, v[10:11]
	ds_read_b128 v[6:9], v6
	v_add_u32_e32 v0, s12, v0
	s_waitcnt lgkmcnt(1)
	global_store_dwordx4 v[14:15], v[2:5], off
	s_nop 1
	v_mad_i64_i32 v[2:3], s[10:11], v0, s35, v[12:13]
	v_add_u32_e32 v0, 0x800, v189
	v_ashrrev_i32_e32 v0, 5, v0
	s_waitcnt lgkmcnt(0)
	global_store_dwordx4 v[2:3], v[6:9], off
	v_mad_u64_u32 v[2:3], s[10:11], v0, s55, v[10:11]
	v_add_u32_e32 v0, s12, v0
	v_mad_i64_i32 v[14:15], s[10:11], v0, s35, v[12:13]
	v_add_u32_e32 v0, 0x900, v189
	ds_read_b128 v[2:5], v2
	v_ashrrev_i32_e32 v0, 5, v0
	v_mad_u64_u32 v[6:7], s[10:11], v0, s55, v[10:11]
	ds_read_b128 v[6:9], v6
	v_add_u32_e32 v0, s12, v0
	s_waitcnt lgkmcnt(1)
	global_store_dwordx4 v[14:15], v[2:5], off
	s_nop 1
	v_mad_i64_i32 v[2:3], s[10:11], v0, s35, v[12:13]
	v_add_u32_e32 v0, 0xa00, v189
	v_ashrrev_i32_e32 v0, 5, v0
	s_waitcnt lgkmcnt(0)
	global_store_dwordx4 v[2:3], v[6:9], off
	v_mad_u64_u32 v[2:3], s[10:11], v0, s55, v[10:11]
	v_add_u32_e32 v0, s12, v0
	v_mad_i64_i32 v[14:15], s[10:11], v0, s35, v[12:13]
	v_add_u32_e32 v0, 0xb00, v189
	ds_read_b128 v[2:5], v2
	v_ashrrev_i32_e32 v0, 5, v0
	v_mad_u64_u32 v[6:7], s[10:11], v0, s55, v[10:11]
	ds_read_b128 v[6:9], v6
	v_add_u32_e32 v0, s12, v0
	s_waitcnt lgkmcnt(1)
	global_store_dwordx4 v[14:15], v[2:5], off
	s_nop 1
	v_mad_i64_i32 v[2:3], s[10:11], v0, s35, v[12:13]
	v_add_u32_e32 v0, 0xc00, v189
	v_ashrrev_i32_e32 v0, 5, v0
	s_waitcnt lgkmcnt(0)
	global_store_dwordx4 v[2:3], v[6:9], off
	v_mad_u64_u32 v[2:3], s[10:11], v0, s55, v[10:11]
	v_add_u32_e32 v0, s12, v0
	v_mad_i64_i32 v[14:15], s[10:11], v0, s35, v[12:13]
	v_add_u32_e32 v0, 0xd00, v189
	ds_read_b128 v[2:5], v2
	v_ashrrev_i32_e32 v0, 5, v0
	v_mad_u64_u32 v[6:7], s[10:11], v0, s55, v[10:11]
	ds_read_b128 v[6:9], v6
	v_add_u32_e32 v0, s12, v0
	s_waitcnt lgkmcnt(1)
	global_store_dwordx4 v[14:15], v[2:5], off
	s_nop 1
	v_mad_i64_i32 v[2:3], s[10:11], v0, s35, v[12:13]
	v_add_u32_e32 v0, 0xe00, v189
	v_ashrrev_i32_e32 v0, 5, v0
	s_waitcnt lgkmcnt(0)
	global_store_dwordx4 v[2:3], v[6:9], off
	v_mad_u64_u32 v[2:3], s[10:11], v0, s55, v[10:11]
	ds_read_b128 v[2:5], v2
	v_add_u32_e32 v0, s12, v0
	v_mad_i64_i32 v[14:15], s[10:11], v0, s35, v[12:13]
	v_add_u32_e32 v0, 0xf00, v189
	v_ashrrev_i32_e32 v0, 5, v0
	v_mad_u64_u32 v[6:7], s[10:11], v0, s55, v[10:11]
	ds_read_b128 v[6:9], v6
	v_add_u32_e32 v0, s12, v0
	s_waitcnt lgkmcnt(1)
	global_store_dwordx4 v[14:15], v[2:5], off
	s_nop 1
	v_mad_i64_i32 v[2:3], s[10:11], v0, s35, v[12:13]
	v_readlane_b32 s10, v252, 12
	s_add_i32 s22, s22, s10
	v_readlane_b32 s10, v252, 38
	s_cmp_ge_i32 s22, s10
	s_waitcnt lgkmcnt(0)
	global_store_dwordx4 v[2:3], v[6:9], off
	s_barrier
	s_cbranch_scc0 .LBB0_230

; #define LAS __attribute__((address_space(3)))
;     ...
;   const int lane = tid & 63, wid = __builtin_amdgcn_readfirstlane(tid >> 6), wr = wid >> 1, wc = wid & 1;
;   const int m0 = mt * 128, n0 = nt * 256;
;   const int r = lane & 31, h = lane >> 5, key = (r >> 2) & 3;
;   constexpr int STG = 24576;
;   const int rowl = lane >> 2, cch = (lane & 3) ^ ((lane >> 4) & 3);
;   const unsigned voffA = (unsigned)(rowl * lda * 2 + cch * 16), voffB = (unsigned)(rowl * K * 2 + cch * 16);
;   const char* Abase = (const char*)(A + (size_t)m0 * lda) + (size_t)(wid * 2) * 32 * lda;
;   const char* Bbase = (const char*)(Bt + (size_t)n0 * K) + (size_t)(wid * 4) * 32 * K;
;   const size_t ablk = (size_t)32 * lda, bblk = (size_t)32 * K;
;   LAS char* lds = (LAS char*)smem;
;   LAS char* ldsA = lds + (wid * 2) * 1024;
;   LAS char* ldsB = lds + 8192 + (wid * 4) * 1024;
;     ...
;   const int x0 = ((0 + h) ^ key) * 16, x1 = ((2 + h) ^ key) * 16;
;   const int a_rd = (wr * 64 + r) * 64, b_rd = 8192 + (wc * 128 + r) * 64;
;   f32x16 acc[2][4];
; #pragma unroll
;   for (int i = 0; i < 2; ++i)
; #pragma unroll
;     for (int j = 0; j < 4; ++j)
; #pragma unroll
;       for (int e = 0; e < 16; ++e) acc[i][j][e] = 0.f;
;   const int nk = K >> 5;
;   DMA_STEP_(0, 0);
;   DMA_STEP_(1, STG);
;   asm volatile("s_waitcnt vmcnt(6)" ::: "memory");
;   __builtin_amdgcn_s_barrier();
;   asm volatile("" ::: "memory");
; __global__ void __launch_bounds__(256, 2) fwd_kernel(Params p) {
;     ...
;       for (int j = slot; j < nmt * 4 / NX; j += nslot) { int mt, nt; gemm_tile_of(j, xcd, NX, 4, 4, mt, nt);
;         gemm_tile256<0>(GB, 2816, Wt, 2816, mt, nt, smem, tid, ea); }
.LBB0_243:
	s_ashr_i32 s10, s29, 31
	s_lshr_b32 s10, s10, 27
	s_add_i32 s10, s29, s10
	s_ashr_i32 s10, s10, 5
	v_readlane_b32 s11, v252, 18
	s_lshl_b32 s11, s10, s11
	v_readlane_b32 s16, v252, 41
	s_add_i32 s11, s11, s16
	s_lshl_b32 s16, s29, 7
	v_mov_b32_e32 v189, v188
	s_lshl_b32 s11, s11, 10
	s_and_b32 s16, s16, 0x380
	s_or_b32 s40, s11, s16
	v_readfirstlane_b32 s42, v189
	s_lshl_b32 s10, s10, 10
	s_lshl_b32 s11, s29, 5
	s_ashr_i32 s44, s42, 6
	s_sub_i32 s10, s11, s10
	s_and_b32 s16, s10, 0xffffff00
	s_lshl_b32 s10, s44, 1
	s_mul_hi_i32 s45, s10, 0x16000
	s_lshl_b32 s10, s44, 2
	s_mov_b32 s47, 0
	s_lshl_b32 s10, s44, 12
	s_add_i32 s43, s10, 16
	s_ashr_i32 s10, s42, 1
	v_and_b32_e32 v0, 31, v189
	s_andn2_b32 s10, s10, 63
	v_or_b32_e32 v197, s10, v0
	s_lshl_b32 s10, s44, 7
	s_ashr_i32 s17, s16, 31
	s_add_i32 s56, s43, 0x2000
	s_and_b32 s42, s10, 0x80
	s_mul_i32 s57, s40, 0x1600
	s_mul_hi_i32 s10, s40, 0x1600
	s_add_u32 s57, s23, s57
	s_mul_i32 s11, s44, 0x2c000
	s_addc_u32 s58, s28, s10
	s_add_u32 s10, s57, s11
	s_addc_u32 s11, s58, s45
	s_mul_i32 s57, s16, 64
	s_mov_b32 s45, 0
	s_add_u32 s57, s19, s57
	s_mul_i32 s46, s44, 0x1000
	s_addc_u32 s45, s20, s45
	s_add_u32 s46, s57, s46
	v_bfe_u32 v2, v189, 2, 4
	v_lshlrev_b32_e32 v3, 4, v189
	s_addc_u32 s47, s45, s47
	s_lshl_b32 s44, s44, 11
	v_xor_b32_e32 v3, v3, v189
	v_mul_u32_u24_e32 v2, 0x1600, v2
	s_sub_i32 s44, s43, s44
	v_or_b32_e32 v5, s42, v0
	v_and_or_b32 v0, v3, 48, v2
	v_bfe_u32 v10, v189, 2, 4
	v_lshlrev_b32_e32 v10, 6, v10
	v_and_or_b32 v10, v3, 48, v10
	v_mov_b32_e32 v11, 0
	s_mov_b32 m0, s44
	v_lshl_add_u64 v[192:193], s[10:11], 0, v[0:1]
	global_load_lds_dwordx4 v0, s[10:11]
	s_mov_b64 s[10:11], 0x16000
	v_lshl_add_u64 v[2:3], v[192:193], 0, s[10:11]
	s_add_i32 m0, s44, 0x400
	v_lshl_add_u64 v[194:195], s[46:47], 0, v[10:11]
	global_load_lds_dwordx4 v[2:3], off
	s_mov_b32 m0, s56
	s_nop 0
	global_load_lds_dwordx4 v[194:195], off
	global_load_lds_dwordx4 v[194:195], off offset:1024
	global_load_lds_dwordx4 v[194:195], off offset:2048
	global_load_lds_dwordx4 v[194:195], off offset:3072
	s_mov_b64 s[10:11], 0x2c000
	s_mov_b64 s[10:11], 0x42000
	s_mov_b64 s[10:11], 0x16040
	s_add_i32 m0, s44, 0x6000
	v_lshl_add_u64 v[2:3], v[192:193], 0, 64
	global_load_lds_dwordx4 v[2:3], off
	v_lshl_add_u64 v[2:3], v[192:193], 0, s[10:11]
	s_add_i32 m0, s44, 0x6400
	v_bfe_u32 v196, v189, 5, 1
	global_load_lds_dwordx4 v[2:3], off
	s_add_i32 m0, s43, 0x8000
	s_mov_b32 s100, 0x10000
	v_lshl_add_u64 v[2:3], v[194:195], 0, s[100:101]
	global_load_lds_dwordx4 v[2:3], off
	global_load_lds_dwordx4 v[2:3], off offset:1024
	global_load_lds_dwordx4 v[2:3], off offset:2048
	global_load_lds_dwordx4 v[2:3], off offset:3072
	s_mov_b64 s[10:11], 0x2c040
	s_mov_b64 s[10:11], 0x42040
	v_lshlrev_b32_e32 v218, 6, v5
	v_bfe_u32 v5, v189, 2, 2
	v_lshrrev_b32_e32 v4, 2, v189
	s_lshl_b32 s100, s100, 1
	v_lshl_add_u64 v[194:195], v[194:195], 0, s[100:101]
	s_waitcnt vmcnt(6)
	s_barrier
	v_bitop3_b32 v2, v196, v5, 2 bitop3:0x36
	v_bitop3_b32 v0, v196, v4, 3 bitop3:0x78
	v_lshlrev_b32_e32 v220, 4, v2
	v_mov_b32_e32 v2, 0
	s_mov_b32 s41, 1
	v_lshlrev_b32_e32 v219, 6, v197
	v_lshlrev_b32_e32 v0, 4, v0
	s_mov_b32 s46, 0
	s_mov_b32 s45, 0xc000
	v_mov_b32_e32 v3, v2
	v_mov_b32_e32 v4, v2
	v_mov_b32_e32 v5, v2
	v_mov_b32_e32 v6, v2
	v_mov_b32_e32 v7, v2
	v_mov_b32_e32 v8, v2
	v_mov_b32_e32 v9, v2
	v_mov_b32_e32 v10, v2
	v_mov_b32_e32 v11, v2
	v_mov_b32_e32 v12, v2
	v_mov_b32_e32 v13, v2
	v_mov_b32_e32 v14, v2
	v_mov_b32_e32 v15, v2
	v_mov_b32_e32 v16, v2
	v_mov_b32_e32 v17, v2
	v_mov_b32_e32 v18, v2
	v_mov_b32_e32 v19, v2
	v_mov_b32_e32 v20, v2
	v_mov_b32_e32 v21, v2
	v_mov_b32_e32 v22, v2
	v_mov_b32_e32 v23, v2
	v_mov_b32_e32 v24, v2
	v_mov_b32_e32 v25, v2
	v_mov_b32_e32 v26, v2
	v_mov_b32_e32 v27, v2
	v_mov_b32_e32 v28, v2
	v_mov_b32_e32 v29, v2
	v_mov_b32_e32 v30, v2
	v_mov_b32_e32 v31, v2
	v_mov_b32_e32 v32, v2
	v_mov_b32_e32 v33, v2
	v_mov_b32_e32 v50, v2
	v_mov_b32_e32 v51, v2
	v_mov_b32_e32 v52, v2
	v_mov_b32_e32 v53, v2
	v_mov_b32_e32 v54, v2
	v_mov_b32_e32 v55, v2
	v_mov_b32_e32 v56, v2
	v_mov_b32_e32 v57, v2
	v_mov_b32_e32 v58, v2
	v_mov_b32_e32 v59, v2
	v_mov_b32_e32 v60, v2
	v_mov_b32_e32 v61, v2
	v_mov_b32_e32 v62, v2
	v_mov_b32_e32 v63, v2
	v_mov_b32_e32 v64, v2
	v_mov_b32_e32 v65, v2
	v_mov_b32_e32 v82, v2
	v_mov_b32_e32 v83, v2
	v_mov_b32_e32 v84, v2
	v_mov_b32_e32 v85, v2
	v_mov_b32_e32 v86, v2
	v_mov_b32_e32 v87, v2
	v_mov_b32_e32 v88, v2
	v_mov_b32_e32 v89, v2
	v_mov_b32_e32 v90, v2
	v_mov_b32_e32 v91, v2
	v_mov_b32_e32 v92, v2
	v_mov_b32_e32 v93, v2
	v_mov_b32_e32 v94, v2
	v_mov_b32_e32 v95, v2
	v_mov_b32_e32 v96, v2
	v_mov_b32_e32 v97, v2
	v_mov_b32_e32 v34, v2
	v_mov_b32_e32 v35, v2
	v_mov_b32_e32 v36, v2
	v_mov_b32_e32 v37, v2
	v_mov_b32_e32 v38, v2
	v_mov_b32_e32 v39, v2
	v_mov_b32_e32 v40, v2
	v_mov_b32_e32 v41, v2
	v_mov_b32_e32 v42, v2
	v_mov_b32_e32 v43, v2
	v_mov_b32_e32 v44, v2
	v_mov_b32_e32 v45, v2
	v_mov_b32_e32 v46, v2
	v_mov_b32_e32 v47, v2
	v_mov_b32_e32 v48, v2
	v_mov_b32_e32 v49, v2
	v_mov_b32_e32 v66, v2
	v_mov_b32_e32 v67, v2
	v_mov_b32_e32 v68, v2
	v_mov_b32_e32 v69, v2
	v_mov_b32_e32 v70, v2
	v_mov_b32_e32 v71, v2
	v_mov_b32_e32 v72, v2
	v_mov_b32_e32 v73, v2
	v_mov_b32_e32 v74, v2
	v_mov_b32_e32 v75, v2
	v_mov_b32_e32 v76, v2
	v_mov_b32_e32 v77, v2
	v_mov_b32_e32 v78, v2
	v_mov_b32_e32 v79, v2
	v_mov_b32_e32 v80, v2
	v_mov_b32_e32 v81, v2
	v_mov_b32_e32 v98, v2
	v_mov_b32_e32 v99, v2
	v_mov_b32_e32 v100, v2
	v_mov_b32_e32 v101, v2
	v_mov_b32_e32 v102, v2
	v_mov_b32_e32 v103, v2
	v_mov_b32_e32 v104, v2
	v_mov_b32_e32 v105, v2
	v_mov_b32_e32 v106, v2
	v_mov_b32_e32 v107, v2
	v_mov_b32_e32 v108, v2
	v_mov_b32_e32 v109, v2
	v_mov_b32_e32 v110, v2
	v_mov_b32_e32 v111, v2
	v_mov_b32_e32 v112, v2
	v_mov_b32_e32 v113, v2
	v_mov_b32_e32 v114, v2
	v_mov_b32_e32 v115, v2
	v_mov_b32_e32 v116, v2
	v_mov_b32_e32 v117, v2
	v_mov_b32_e32 v118, v2
	v_mov_b32_e32 v119, v2
	v_mov_b32_e32 v120, v2
	v_mov_b32_e32 v121, v2
	v_mov_b32_e32 v122, v2
	v_mov_b32_e32 v123, v2
	v_mov_b32_e32 v124, v2
	v_mov_b32_e32 v125, v2
	v_mov_b32_e32 v126, v2
	v_mov_b32_e32 v127, v2
	v_mov_b32_e32 v128, v2
	v_mov_b32_e32 v129, v2
; #define LAS __attribute__((address_space(3)))
; DI f32x16 mfma32(bf16x8 a, bf16x8 b, f32x16 c) { return __builtin_amdgcn_mfma_f32_32x32x16_bf16(a, b, c, 0, 0, 0); }
;     ...
;   for (int kt = 0; kt < nk; ++kt) {
;     const int kn = (kt + 2 < nk) ? (kt + 2) : (nk - 1);
;     const LAS char* cur = lds + s0;
;     bf16x8 af[2][2], bfr[2][4];
; #pragma unroll
;     for (int kk = 0; kk < 2; ++kk) {
;       const int xo = kk ? x1 : x0;
;       af[kk][0] = *(const LAS bf16x8*)(cur + a_rd + xo);
;       bfr[kk][0] = *(const LAS bf16x8*)(cur + b_rd + xo);
;       bfr[kk][1] = *(const LAS bf16x8*)(cur + b_rd + 2048 + xo);
;       af[kk][1] = *(const LAS bf16x8*)(cur + a_rd + 2048 + xo);
;       bfr[kk][2] = *(const LAS bf16x8*)(cur + b_rd + 4096 + xo);
;       bfr[kk][3] = *(const LAS bf16x8*)(cur + b_rd + 6144 + xo);
;     }
;     DMA_STEP_(kn, s2);
; #pragma unroll
;     for (int kk = 0; kk < 2; ++kk) {
;       acc[0][0] = mfma32(bfr[kk][0], af[kk][0], acc[0][0]); acc[0][1] = mfma32(bfr[kk][1], af[kk][0], acc[0][1]);
;       acc[1][0] = mfma32(bfr[kk][0], af[kk][1], acc[1][0]); acc[1][1] = mfma32(bfr[kk][1], af[kk][1], acc[1][1]);
;       acc[0][2] = mfma32(bfr[kk][2], af[kk][0], acc[0][2]); acc[0][3] = mfma32(bfr[kk][3], af[kk][0], acc[0][3]);
;       acc[1][2] = mfma32(bfr[kk][2], af[kk][1], acc[1][2]); acc[1][3] = mfma32(bfr[kk][3], af[kk][1], acc[1][3]);
;     }
;     __builtin_amdgcn_sched_group_barrier(0x100, 12, 0);
;     __builtin_amdgcn_sched_group_barrier(0x010, 6, 0);
;     __builtin_amdgcn_sched_group_barrier(0x008, 16, 0);
;     asm volatile("s_waitcnt vmcnt(6) lgkmcnt(0)" ::: "memory");
;     __builtin_amdgcn_s_barrier();
;     asm volatile("" ::: "memory");
;     s0 = (s0 == 2 * STG) ? 0 : s0 + STG;
;     s2 = (s2 == 2 * STG) ? 0 : s2 + STG;
.LBB0_244:
	s_add_i32 s11, s46, 16
	s_add_i32 s10, s41, -1
	v_add_u32_e32 v142, s11, v218
	v_add_u32_e32 v140, v142, v0
	s_min_u32 s10, s10, 0x55
	ds_read_b128 v[182:185], v140 offset:8192
	ds_read_b128 v[178:181], v140 offset:10240
	ds_read_b128 v[174:177], v140 offset:12288
	ds_read_b128 v[170:173], v140 offset:14336
	s_lshl_b32 s70, s10, 6
	v_add_u32_e32 v138, s11, v219
	v_lshl_add_u64 v[222:223], v[192:193], 0, s[70:71]
	s_add_i32 s10, s44, s45
	v_add_u32_e32 v139, v138, v0
	v_add_u32_e32 v143, v138, v220
	v_add_u32_e32 v150, v142, v220
	v_lshl_add_u64 v[224:225], v[222:223], 0, s[24:25]
	s_mov_b32 m0, s10
	ds_read_b128 v[158:161], v139
	ds_read_b128 v[162:165], v139 offset:2048
	ds_read_b128 v[138:141], v143
	ds_read_b128 v[166:169], v150 offset:8192
	ds_read_b128 v[154:157], v150 offset:10240
	ds_read_b128 v[142:145], v143 offset:2048
	ds_read_b128 v[146:149], v150 offset:12288
	ds_read_b128 v[150:153], v150 offset:14336
	global_load_lds_dwordx4 v[224:225], off
	v_lshl_add_u64 v[222:223], v[222:223], 0, s[98:99]
	s_add_i32 m0, s10, 0x400
	s_add_i32 s10, s43, s45
	global_load_lds_dwordx4 v[222:223], off
	s_mul_i32 s100, s70, 0x400
	v_lshl_add_u64 v[224:225], v[194:195], 0, s[100:101]
	s_add_i32 m0, s10, 0x2000
	s_nop 0
	global_load_lds_dwordx4 v[224:225], off
	global_load_lds_dwordx4 v[224:225], off offset:1024
	global_load_lds_dwordx4 v[224:225], off offset:2048
	global_load_lds_dwordx4 v[224:225], off offset:3072
	s_add_i32 s10, s46, 0x6000
	s_waitcnt lgkmcnt(0)
	v_mfma_f32_32x32x16_bf16 v[114:129], v[182:185], v[158:161], v[114:129]
	s_cmpk_lg_u32 s46, 0xc000
	s_cselect_b32 s46, s10, 0
	s_add_i32 s10, s45, 0x6000
	s_cmpk_lg_u32 s45, 0xc000
	s_cselect_b32 s45, s10, 0
	s_add_i32 s10, s46, 16
	s_waitcnt vmcnt(6) lgkmcnt(0)
	v_mfma_f32_32x32x16_bf16 v[98:113], v[178:181], v[158:161], v[98:113]
	s_barrier
	v_mfma_f32_32x32x16_bf16 v[66:81], v[182:185], v[162:165], v[66:81]
	v_mfma_f32_32x32x16_bf16 v[34:49], v[178:181], v[162:165], v[34:49]
	v_mfma_f32_32x32x16_bf16 v[82:97], v[174:177], v[158:161], v[82:97]
	v_mfma_f32_32x32x16_bf16 v[50:65], v[170:173], v[158:161], v[50:65]
	v_mfma_f32_32x32x16_bf16 v[18:33], v[174:177], v[162:165], v[18:33]
	v_mfma_f32_32x32x16_bf16 v[2:17], v[170:173], v[162:165], v[2:17]
	v_mfma_f32_32x32x16_bf16 v[114:129], v[166:169], v[138:141], v[114:129]
	v_mfma_f32_32x32x16_bf16 v[98:113], v[154:157], v[138:141], v[98:113]
	v_mfma_f32_32x32x16_bf16 v[66:81], v[166:169], v[142:145], v[66:81]
	v_mfma_f32_32x32x16_bf16 v[34:49], v[154:157], v[142:145], v[34:49]
	v_mfma_f32_32x32x16_bf16 v[82:97], v[146:149], v[138:141], v[82:97]
	v_mfma_f32_32x32x16_bf16 v[50:65], v[150:153], v[138:141], v[50:65]
	v_add_u32_e32 v138, s10, v219
	v_add_u32_e32 v139, v138, v0
	v_mfma_f32_32x32x16_bf16 v[18:33], v[146:149], v[142:145], v[18:33]
	v_mfma_f32_32x32x16_bf16 v[2:17], v[150:153], v[142:145], v[2:17]
	v_add_u32_e32 v142, s10, v218
	s_min_u32 s10, s41, 0x55
	s_lshl_b32 s70, s10, 6
	v_lshl_add_u64 v[222:223], v[192:193], 0, s[70:71]
	s_add_i32 s10, s44, s45
	v_add_u32_e32 v140, v142, v0
	v_add_u32_e32 v143, v138, v220
	v_add_u32_e32 v150, v142, v220
	v_lshl_add_u64 v[224:225], v[222:223], 0, s[24:25]
	s_mov_b32 m0, s10
	ds_read_b128 v[158:161], v139
	ds_read_b128 v[182:185], v140 offset:8192
	ds_read_b128 v[178:181], v140 offset:10240
	ds_read_b128 v[162:165], v139 offset:2048
	ds_read_b128 v[174:177], v140 offset:12288
	ds_read_b128 v[170:173], v140 offset:14336
	ds_read_b128 v[138:141], v143
	ds_read_b128 v[166:169], v150 offset:8192
	ds_read_b128 v[154:157], v150 offset:10240
	ds_read_b128 v[142:145], v143 offset:2048
	ds_read_b128 v[146:149], v150 offset:12288
	ds_read_b128 v[150:153], v150 offset:14336
	global_load_lds_dwordx4 v[224:225], off
	v_lshl_add_u64 v[222:223], v[222:223], 0, s[98:99]
	s_add_i32 m0, s10, 0x400
	s_add_i32 s10, s43, s45
	global_load_lds_dwordx4 v[222:223], off
	s_mul_i32 s100, s70, 0x400
	v_lshl_add_u64 v[224:225], v[194:195], 0, s[100:101]
	s_add_i32 m0, s10, 0x2000
	s_nop 0
	global_load_lds_dwordx4 v[224:225], off
	global_load_lds_dwordx4 v[224:225], off offset:1024
	global_load_lds_dwordx4 v[224:225], off offset:2048
	global_load_lds_dwordx4 v[224:225], off offset:3072
	s_add_i32 s10, s46, 0x6000
	s_waitcnt lgkmcnt(0)
	v_mfma_f32_32x32x16_bf16 v[114:129], v[182:185], v[158:161], v[114:129]
	s_cmpk_lg_u32 s46, 0xc000
	s_cselect_b32 s46, s10, 0
	s_add_i32 s10, s45, 0x6000
	s_waitcnt vmcnt(6) lgkmcnt(0)
	s_barrier
	s_cmpk_lg_u32 s45, 0xc000
	v_mfma_f32_32x32x16_bf16 v[98:113], v[178:181], v[158:161], v[98:113]
	s_cselect_b32 s45, s10, 0
	s_add_i32 s41, s41, 2
	s_cmpk_lg_i32 s41, 0x59
	v_mfma_f32_32x32x16_bf16 v[66:81], v[182:185], v[162:165], v[66:81]
	v_mfma_f32_32x32x16_bf16 v[34:49], v[178:181], v[162:165], v[34:49]
	v_mfma_f32_32x32x16_bf16 v[82:97], v[174:177], v[158:161], v[82:97]
	v_mfma_f32_32x32x16_bf16 v[50:65], v[170:173], v[158:161], v[50:65]
	v_mfma_f32_32x32x16_bf16 v[18:33], v[174:177], v[162:165], v[18:33]
	v_mfma_f32_32x32x16_bf16 v[2:17], v[170:173], v[162:165], v[2:17]
	v_mfma_f32_32x32x16_bf16 v[114:129], v[166:169], v[138:141], v[114:129]
	v_mfma_f32_32x32x16_bf16 v[98:113], v[154:157], v[138:141], v[98:113]
	v_mfma_f32_32x32x16_bf16 v[66:81], v[166:169], v[142:145], v[66:81]
	v_mfma_f32_32x32x16_bf16 v[34:49], v[154:157], v[142:145], v[34:49]
	v_mfma_f32_32x32x16_bf16 v[82:97], v[146:149], v[138:141], v[82:97]
	v_mfma_f32_32x32x16_bf16 v[50:65], v[150:153], v[138:141], v[50:65]
	v_mfma_f32_32x32x16_bf16 v[18:33], v[146:149], v[142:145], v[18:33]
	v_mfma_f32_32x32x16_bf16 v[2:17], v[150:153], v[142:145], v[2:17]
	s_cbranch_scc1 .LBB0_244
; DI unsigned pk2(float a, float b) { f32x2 v = {a, b}; bf2_t r = __builtin_convertvector(v, bf2_t); return __builtin_bit_cast(unsigned, r); }
;     ...
;   {
;     const int h = lane >> 5, cl = lane & 31;
; #pragma unroll
;     for (int i = 0; i < 2; ++i)
; #pragma unroll
;       for (int j = 0; j < 4; ++j)
; #pragma unroll
;         for (int g = 0; g < 4; ++g) {
;           u32x2 w; w.x = pk2(acc[i][j][4 * g], acc[i][j][4 * g + 1]); w.y = pk2(acc[i][j][4 * g + 2], acc[i][j][4 * g + 3]);
;           *(u32x2*)(smem + (wr * 64 + i * 32 + cl) * 528 + (wc * 128 + j * 32 + 8 * g + 4 * h) * 2) = w;
;         }
;   }
;   __syncthreads();
	v_mul_lo_u32 v0, v197, s55
	v_add_u32_e32 v0, 16, v0
	s_nop 1
	v_cvt_pk_bf16_f32 v114, v114, v115
	v_cvt_pk_bf16_f32 v115, v116, v117
	v_lshlrev_b32_e32 v116, 3, v196
	s_lshl_b32 s10, s42, 1
	v_add3_u32 v0, v0, v116, s10
	v_cvt_pk_bf16_f32 v116, v118, v119
	v_cvt_pk_bf16_f32 v117, v120, v121
	v_cvt_pk_bf16_f32 v98, v98, v99
	v_cvt_pk_bf16_f32 v99, v100, v101
	v_cvt_pk_bf16_f32 v100, v102, v103
	v_cvt_pk_bf16_f32 v101, v104, v105
	v_cvt_pk_bf16_f32 v82, v82, v83
	v_cvt_pk_bf16_f32 v83, v84, v85
	v_cvt_pk_bf16_f32 v84, v86, v87
	v_cvt_pk_bf16_f32 v85, v88, v89
	v_cvt_pk_bf16_f32 v50, v50, v51
	v_cvt_pk_bf16_f32 v51, v52, v53
	v_cvt_pk_bf16_f32 v52, v54, v55
	v_cvt_pk_bf16_f32 v53, v56, v57
	s_waitcnt vmcnt(0)
	s_barrier
	ds_write2_b64 v0, v[114:115], v[116:117] offset1:2
	v_cvt_pk_bf16_f32 v114, v122, v123
	v_cvt_pk_bf16_f32 v115, v124, v125
	v_cvt_pk_bf16_f32 v116, v126, v127
	v_cvt_pk_bf16_f32 v117, v128, v129
	ds_write2_b64 v0, v[98:99], v[100:101] offset0:8 offset1:10
	v_cvt_pk_bf16_f32 v98, v106, v107
	v_cvt_pk_bf16_f32 v99, v108, v109
	v_cvt_pk_bf16_f32 v100, v110, v111
	v_cvt_pk_bf16_f32 v101, v112, v113
	ds_write2_b64 v0, v[82:83], v[84:85] offset0:16 offset1:18
	v_cvt_pk_bf16_f32 v82, v90, v91
	v_cvt_pk_bf16_f32 v83, v92, v93
	v_cvt_pk_bf16_f32 v84, v94, v95
	v_cvt_pk_bf16_f32 v85, v96, v97
	ds_write2_b64 v0, v[50:51], v[52:53] offset0:24 offset1:26
	v_cvt_pk_bf16_f32 v50, v58, v59
	v_cvt_pk_bf16_f32 v51, v60, v61
	v_cvt_pk_bf16_f32 v52, v62, v63
	v_cvt_pk_bf16_f32 v53, v64, v65
	ds_write2_b64 v0, v[114:115], v[116:117] offset0:4 offset1:6
	ds_write2_b64 v0, v[98:99], v[100:101] offset0:12 offset1:14
	ds_write2_b64 v0, v[82:83], v[84:85] offset0:20 offset1:22
	ds_write2_b64 v0, v[50:51], v[52:53] offset0:28 offset1:30
	v_cvt_pk_bf16_f32 v50, v66, v67
	v_cvt_pk_bf16_f32 v51, v68, v69
	v_cvt_pk_bf16_f32 v52, v70, v71
	v_cvt_pk_bf16_f32 v53, v72, v73
	v_add_u32_e32 v0, 0x4000, v0
	v_cvt_pk_bf16_f32 v34, v34, v35
	v_cvt_pk_bf16_f32 v35, v36, v37
	v_cvt_pk_bf16_f32 v36, v38, v39
	v_cvt_pk_bf16_f32 v37, v40, v41
	v_cvt_pk_bf16_f32 v18, v18, v19
	v_cvt_pk_bf16_f32 v19, v20, v21
	v_cvt_pk_bf16_f32 v20, v22, v23
	v_cvt_pk_bf16_f32 v21, v24, v25
	v_cvt_pk_bf16_f32 v2, v2, v3
	v_cvt_pk_bf16_f32 v3, v4, v5
	v_cvt_pk_bf16_f32 v4, v6, v7
	v_cvt_pk_bf16_f32 v5, v8, v9
	ds_write2_b64 v0, v[50:51], v[52:53] offset0:64 offset1:66
	v_cvt_pk_bf16_f32 v50, v74, v75
	v_cvt_pk_bf16_f32 v51, v76, v77
	v_cvt_pk_bf16_f32 v52, v78, v79
	v_cvt_pk_bf16_f32 v53, v80, v81
	ds_write2_b64 v0, v[34:35], v[36:37] offset0:72 offset1:74
	v_cvt_pk_bf16_f32 v34, v42, v43
	v_cvt_pk_bf16_f32 v35, v44, v45
	v_cvt_pk_bf16_f32 v36, v46, v47
	v_cvt_pk_bf16_f32 v37, v48, v49
	ds_write2_b64 v0, v[18:19], v[20:21] offset0:80 offset1:82
	v_cvt_pk_bf16_f32 v18, v26, v27
	v_cvt_pk_bf16_f32 v19, v28, v29
	v_cvt_pk_bf16_f32 v20, v30, v31
	v_cvt_pk_bf16_f32 v21, v32, v33
	ds_write2_b64 v0, v[2:3], v[4:5] offset0:88 offset1:90
	v_cvt_pk_bf16_f32 v2, v10, v11
	v_cvt_pk_bf16_f32 v3, v12, v13
	v_cvt_pk_bf16_f32 v4, v14, v15
	v_cvt_pk_bf16_f32 v5, v16, v17
	s_lshl_b64 s[10:11], s[16:17], 1
	ds_write2_b64 v0, v[50:51], v[52:53] offset0:68 offset1:70
	ds_write2_b64 v0, v[34:35], v[36:37] offset0:76 offset1:78
	ds_write2_b64 v0, v[18:19], v[20:21] offset0:84 offset1:86
	ds_write2_b64 v0, v[2:3], v[4:5] offset0:92 offset1:94
	s_waitcnt vmcnt(0) lgkmcnt(0)
	s_barrier
; #define GAS __attribute__((address_space(1)))
;     ...
;   int tid2 = tid; asm volatile("" : "+v"(tid2));
;   if (EPI == 0) {
; #pragma unroll
;     for (int i = 0; i < 16; ++i) {
;       const int id = tid2 + 256 * i, r = id >> 5, c8 = (id & 31) * 8;
;       const u32x4 v = *(const u32x4*)(smem + r * 528 + c8 * 2);
;       *(GAS u32x4*)(ea.out + (size_t)(m0 + r) * ea.ldo + n0 + c8) = v;
;     }
	s_add_u32 s10, s21, s10
	v_lshlrev_b32_e32 v0, 4, v189
	v_and_b32_e32 v0, 0x1f0, v0
	s_addc_u32 s11, s22, s11
	v_add_u32_e32 v10, 16, v0
	v_lshl_add_u64 v[12:13], s[10:11], 0, v[0:1]
	v_ashrrev_i32_e32 v0, 5, v189
	v_mad_u64_u32 v[2:3], s[10:11], v0, s55, v[10:11]
	ds_read_b128 v[2:5], v2
	v_add_u32_e32 v6, s40, v0
	v_ashrrev_i32_e32 v7, 31, v6
	v_add_u32_e32 v0, 0x100, v189
	v_lshlrev_b64 v[6:7], 11, v[6:7]
	v_ashrrev_i32_e32 v0, 5, v0
	v_lshl_add_u64 v[14:15], v[12:13], 0, v[6:7]
	v_mad_u64_u32 v[6:7], s[10:11], v0, s55, v[10:11]
	ds_read_b128 v[6:9], v6
	s_waitcnt lgkmcnt(1)
	global_store_dwordx4 v[14:15], v[2:5], off
	s_nop 1
	v_add_u32_e32 v2, s40, v0
	v_ashrrev_i32_e32 v3, 31, v2
	v_lshlrev_b64 v[2:3], 11, v[2:3]
	v_add_u32_e32 v0, 0x200, v189
	v_lshl_add_u64 v[2:3], v[12:13], 0, v[2:3]
	v_ashrrev_i32_e32 v0, 5, v0
	s_waitcnt lgkmcnt(0)
	global_store_dwordx4 v[2:3], v[6:9], off
	v_mad_u64_u32 v[2:3], s[10:11], v0, s55, v[10:11]
	ds_read_b128 v[2:5], v2
	v_add_u32_e32 v6, s40, v0
	v_ashrrev_i32_e32 v7, 31, v6
	v_add_u32_e32 v0, 0x300, v189
	v_lshlrev_b64 v[6:7], 11, v[6:7]
	v_ashrrev_i32_e32 v0, 5, v0
	v_lshl_add_u64 v[14:15], v[12:13], 0, v[6:7]
	v_mad_u64_u32 v[6:7], s[10:11], v0, s55, v[10:11]
	ds_read_b128 v[6:9], v6
	s_waitcnt lgkmcnt(1)
	global_store_dwordx4 v[14:15], v[2:5], off
	s_nop 1
	v_add_u32_e32 v2, s40, v0
	v_ashrrev_i32_e32 v3, 31, v2
	v_lshlrev_b64 v[2:3], 11, v[2:3]
	v_add_u32_e32 v0, 0x400, v189
	v_lshl_add_u64 v[2:3], v[12:13], 0, v[2:3]
	v_ashrrev_i32_e32 v0, 5, v0
	s_waitcnt lgkmcnt(0)
	global_store_dwordx4 v[2:3], v[6:9], off
	v_mad_u64_u32 v[2:3], s[10:11], v0, s55, v[10:11]
	ds_read_b128 v[2:5], v2
	v_add_u32_e32 v6, s40, v0
	v_ashrrev_i32_e32 v7, 31, v6
	v_add_u32_e32 v0, 0x500, v189
	v_lshlrev_b64 v[6:7], 11, v[6:7]
	v_ashrrev_i32_e32 v0, 5, v0
	v_lshl_add_u64 v[14:15], v[12:13], 0, v[6:7]
	v_mad_u64_u32 v[6:7], s[10:11], v0, s55, v[10:11]
	ds_read_b128 v[6:9], v6
	s_waitcnt lgkmcnt(1)
	global_store_dwordx4 v[14:15], v[2:5], off
	s_nop 1
	v_add_u32_e32 v2, s40, v0
	v_ashrrev_i32_e32 v3, 31, v2
	v_lshlrev_b64 v[2:3], 11, v[2:3]
	v_add_u32_e32 v0, 0x600, v189
	v_lshl_add_u64 v[2:3], v[12:13], 0, v[2:3]
	v_ashrrev_i32_e32 v0, 5, v0
	s_waitcnt lgkmcnt(0)
	global_store_dwordx4 v[2:3], v[6:9], off
	v_mad_u64_u32 v[2:3], s[10:11], v0, s55, v[10:11]
	ds_read_b128 v[2:5], v2
	v_add_u32_e32 v6, s40, v0
	v_ashrrev_i32_e32 v7, 31, v6
	v_add_u32_e32 v0, 0x700, v189
	v_lshlrev_b64 v[6:7], 11, v[6:7]
	v_ashrrev_i32_e32 v0, 5, v0
	v_lshl_add_u64 v[14:15], v[12:13], 0, v[6:7]
	v_mad_u64_u32 v[6:7], s[10:11], v0, s55, v[10:11]
	ds_read_b128 v[6:9], v6
	s_waitcnt lgkmcnt(1)
	global_store_dwordx4 v[14:15], v[2:5], off
	s_nop 1
	v_add_u32_e32 v2, s40, v0
	v_ashrrev_i32_e32 v3, 31, v2
	v_lshlrev_b64 v[2:3], 11, v[2:3]
	v_add_u32_e32 v0, 0x800, v189
	v_lshl_add_u64 v[2:3], v[12:13], 0, v[2:3]
	v_ashrrev_i32_e32 v0, 5, v0
	s_waitcnt lgkmcnt(0)
	global_store_dwordx4 v[2:3], v[6:9], off
	v_mad_u64_u32 v[2:3], s[10:11], v0, s55, v[10:11]
	ds_read_b128 v[2:5], v2
	v_add_u32_e32 v6, s40, v0
	v_ashrrev_i32_e32 v7, 31, v6
	v_add_u32_e32 v0, 0x900, v189
	v_lshlrev_b64 v[6:7], 11, v[6:7]
	v_ashrrev_i32_e32 v0, 5, v0
	v_lshl_add_u64 v[14:15], v[12:13], 0, v[6:7]
	v_mad_u64_u32 v[6:7], s[10:11], v0, s55, v[10:11]
	ds_read_b128 v[6:9], v6
	s_waitcnt lgkmcnt(1)
	global_store_dwordx4 v[14:15], v[2:5], off
	s_nop 1
	v_add_u32_e32 v2, s40, v0
	v_ashrrev_i32_e32 v3, 31, v2
	v_lshlrev_b64 v[2:3], 11, v[2:3]
	v_add_u32_e32 v0, 0xa00, v189
	v_lshl_add_u64 v[2:3], v[12:13], 0, v[2:3]
	v_ashrrev_i32_e32 v0, 5, v0
	s_waitcnt lgkmcnt(0)
	global_store_dwordx4 v[2:3], v[6:9], off
	v_mad_u64_u32 v[2:3], s[10:11], v0, s55, v[10:11]
	ds_read_b128 v[2:5], v2
	v_add_u32_e32 v6, s40, v0
	v_ashrrev_i32_e32 v7, 31, v6
	v_add_u32_e32 v0, 0xb00, v189
	v_lshlrev_b64 v[6:7], 11, v[6:7]
	v_ashrrev_i32_e32 v0, 5, v0
	v_lshl_add_u64 v[14:15], v[12:13], 0, v[6:7]
	v_mad_u64_u32 v[6:7], s[10:11], v0, s55, v[10:11]
	ds_read_b128 v[6:9], v6
	s_waitcnt lgkmcnt(1)
	global_store_dwordx4 v[14:15], v[2:5], off
	s_nop 1
	v_add_u32_e32 v2, s40, v0
	v_ashrrev_i32_e32 v3, 31, v2
	v_lshlrev_b64 v[2:3], 11, v[2:3]
	v_add_u32_e32 v0, 0xc00, v189
	v_lshl_add_u64 v[2:3], v[12:13], 0, v[2:3]
	v_ashrrev_i32_e32 v0, 5, v0
	s_waitcnt lgkmcnt(0)
	global_store_dwordx4 v[2:3], v[6:9], off
	v_mad_u64_u32 v[2:3], s[10:11], v0, s55, v[10:11]
	ds_read_b128 v[2:5], v2
	v_add_u32_e32 v6, s40, v0
	v_ashrrev_i32_e32 v7, 31, v6
	v_add_u32_e32 v0, 0xd00, v189
	v_lshlrev_b64 v[6:7], 11, v[6:7]
	v_ashrrev_i32_e32 v0, 5, v0
	v_lshl_add_u64 v[14:15], v[12:13], 0, v[6:7]
	v_mad_u64_u32 v[6:7], s[10:11], v0, s55, v[10:11]
	ds_read_b128 v[6:9], v6
	s_waitcnt lgkmcnt(1)
	global_store_dwordx4 v[14:15], v[2:5], off
	s_nop 1
	v_add_u32_e32 v2, s40, v0
	v_ashrrev_i32_e32 v3, 31, v2
	v_lshlrev_b64 v[2:3], 11, v[2:3]
	v_add_u32_e32 v0, 0xe00, v189
	v_lshl_add_u64 v[2:3], v[12:13], 0, v[2:3]
	v_ashrrev_i32_e32 v0, 5, v0
	s_waitcnt lgkmcnt(0)
	global_store_dwordx4 v[2:3], v[6:9], off
	v_mad_u64_u32 v[2:3], s[10:11], v0, s55, v[10:11]
	ds_read_b128 v[2:5], v2
	v_add_u32_e32 v6, s40, v0
	v_ashrrev_i32_e32 v7, 31, v6
	v_add_u32_e32 v0, 0xf00, v189
	v_lshlrev_b64 v[6:7], 11, v[6:7]
	v_ashrrev_i32_e32 v0, 5, v0
	v_lshl_add_u64 v[14:15], v[12:13], 0, v[6:7]
	v_mad_u64_u32 v[6:7], s[10:11], v0, s55, v[10:11]
	ds_read_b128 v[6:9], v6
	s_waitcnt lgkmcnt(1)
	global_store_dwordx4 v[14:15], v[2:5], off
	v_readlane_b32 s10, v252, 12
	s_add_i32 s29, s29, s10
	v_add_u32_e32 v2, s40, v0
	v_ashrrev_i32_e32 v3, 31, v2
	v_lshlrev_b64 v[2:3], 11, v[2:3]
	v_lshl_add_u64 v[2:3], v[12:13], 0, v[2:3]
	s_cmp_ge_i32 s29, s18
	s_waitcnt lgkmcnt(0)
	global_store_dwordx4 v[2:3], v[6:9], off
	s_barrier
	s_cbranch_scc0 .LBB0_243

; #define GAS __attribute__((address_space(1)))
; DI unsigned pk2(float a, float b) { f32x2 v = {a, b}; bf2_t r = __builtin_convertvector(v, bf2_t); return __builtin_bit_cast(unsigned, r); }
; DI void wt_item(const float* __restrict__ W, int ldw, int K, bf16_t* __restrict__ Wt, int k0, int d0, int mode, char* smem, int tid) {
;     ...
;   __syncthreads();
; #pragma unroll
;   for (int u = 0; u < 2; ++u) {
;     const int id = tid + 256 * u, j = id >> 3, k8 = (id & 7) * 8;
;     float v[8];
; #pragma unroll
;     for (int e = 0; e < 8; ++e) v[e] = tile[(k8 + e) * 65 + j];
;     u32x4 w; w.x = pk2(v[0], v[1]); w.y = pk2(v[2], v[3]); w.z = pk2(v[4], v[5]); w.w = pk2(v[6], v[7]);
;     *(GAS u32x4*)(Wt + (size_t)(d0 + j) * K + k0 + k8) = w;
;   }
.LBB0_461:
	s_or_b64 exec, exec, s[18:19]
	v_readlane_b32 s10, v250, 18
	ds_write_b32 v66, v0 offset:14560
	ds_write_b32 v66, v7 offset:15600
	v_add_u32_e32 v0, 0x400, v64
	v_readlane_b32 s11, v250, 19
	s_add_u32 s10, s10, s48
	s_waitcnt lgkmcnt(0)
	s_barrier
	ds_read2_b32 v[8:9], v64 offset1:65
	ds_read2_b32 v[10:11], v64 offset0:130 offset1:195
	ds_read2_b32 v[12:13], v0 offset0:4 offset1:69
	ds_read2_b32 v[14:15], v0 offset0:134 offset1:199
	s_addc_u32 s11, s11, s49
	s_cmp_eq_u32 s48, 0x1f90000
	s_cbranch_scc1 .Lmy_wt_new
	s_cmp_eq_u32 s48, 0x2510000
	s_cbranch_scc1 .Lmy_wt_new
	s_cmp_eq_u32 s48, 0x0
	s_cbranch_scc1 .Lmy_wt_new
	s_cmp_eq_u32 s48, 0x2a90000
	s_cbranch_scc1 .Lmy_wt_new
	s_cmp_eq_u32 s48, 0x590000
	s_cbranch_scc1 .Lmy_wt_new
	s_cmp_eq_u32 s48, 0x790000
	s_cbranch_scc1 .Lmy_wt_new
	s_cmp_eq_u32 s48, 0x990000
	s_cbranch_scc1 .Lmy_wt_new
	s_cmp_eq_u32 s48, 0x1490000
	s_cbranch_scc1 .Lmy_wt_new
	s_lshl_b32 s18, s22, 1
	s_add_u32 s18, s10, s18
	s_addc_u32 s19, s11, 0
	v_mov_b32_e32 v7, v1
	v_add_u32_e32 v0, s15, v61
	v_lshl_add_u64 v[16:17], s[18:19], 0, v[6:7]
	v_ashrrev_i32_e32 v7, 31, v0
	s_waitcnt lgkmcnt(0)
	v_cvt_pk_bf16_f32 v8, v8, v9
	v_cvt_pk_bf16_f32 v9, v10, v11
	v_cvt_pk_bf16_f32 v10, v12, v13
	v_cvt_pk_bf16_f32 v11, v14, v15
	v_mul_lo_u32 v7, s46, v7
	v_mul_lo_u32 v14, s47, v0
	v_mad_u64_u32 v[12:13], s[18:19], s46, v0, 0
	v_add3_u32 v13, v13, v7, v14
	ds_read2_b32 v[14:15], v65 offset1:65
	ds_read2_b32 v[18:19], v65 offset0:130 offset1:195
	v_add_u32_e32 v0, 0x400, v65
	ds_read2_b32 v[20:21], v0 offset0:4 offset1:69
	ds_read2_b32 v[22:23], v0 offset0:134 offset1:199
	v_add_u32_e32 v0, s15, v62
	v_lshl_add_u64 v[12:13], v[12:13], 1, v[16:17]
	v_ashrrev_i32_e32 v7, 31, v0
	global_store_dwordx4 v[12:13], v[8:11], off
	v_mul_lo_u32 v7, s46, v7
	v_mad_u64_u32 v[12:13], s[18:19], s46, v0, 0
	s_waitcnt lgkmcnt(0)
	v_cvt_pk_bf16_f32 v8, v14, v15
	v_mul_lo_u32 v14, s47, v0
	v_add3_u32 v13, v13, v7, v14
	v_cvt_pk_bf16_f32 v9, v18, v19
	v_cvt_pk_bf16_f32 v10, v20, v21
	v_cvt_pk_bf16_f32 v11, v22, v23
	v_lshl_add_u64 v[12:13], v[12:13], 1, v[16:17]
	global_store_dwordx4 v[12:13], v[8:11], off
	s_branch .Lmy_wt_done
